# v28 + 22 more m0 writes hoisted above the address VALU (s_nop 0 before LDS-DMA loads in unit prologues removed)
# baseline (speedup 1.0000x reference)
.Lpeel124_mid:
	s_add_i32 s49, 0, 0x18000
	s_add_i32 s50, 0, 0x1c000
	v_add_u32_e32 v164, s49, v159
	v_add_u32_e32 v184, s50, v159
	ds_read_b128 v[128:131], v164
	ds_read_b128 v[132:135], v164 offset:1024
	ds_read_b128 v[152:155], v164 offset:2048
	ds_read_b128 v[164:167], v164 offset:3072
	ds_read_b128 v[172:175], v184
	ds_read_b128 v[176:179], v184 offset:1024
	ds_read_b128 v[180:183], v184 offset:2048
	ds_read_b128 v[184:187], v184 offset:3072
	s_add_u32 s28, s28, 0x40000
	s_addc_u32 s29, s29, 0
	s_mov_b32 m0, s36
	v_lshl_add_u64 v[224:225], s[28:29], 0, v[136:137]
	ds_read_b128 v[188:191], v163 offset:32768
	ds_read_b128 v[192:195], v163 offset:33792
	ds_read_b128 v[196:199], v163 offset:34816
	ds_read_b128 v[200:203], v163 offset:35840
	ds_read_b128 v[204:207], v163 offset:36864
	ds_read_b128 v[208:211], v163 offset:37888
	ds_read_b128 v[212:215], v163 offset:38912
	ds_read_b128 v[216:219], v163 offset:39936
	global_load_lds_dwordx4 v[224:225], off
	s_mov_b32 m0, s37
	v_lshl_add_u64 v[224:225], s[28:29], 0, v[140:141]
	global_load_lds_dwordx4 v[224:225], off
	s_waitcnt vmcnt(8) lgkmcnt(0)
	s_barrier
	v_mfma_f32_16x16x32_bf16 v[124:127], v[128:131], v[188:191], v[124:127]
	v_mfma_f32_16x16x32_bf16 v[120:123], v[152:155], v[188:191], v[120:123]
	v_mfma_f32_16x16x32_bf16 v[108:111], v[128:131], v[196:199], v[108:111]
	v_mfma_f32_16x16x32_bf16 v[104:107], v[152:155], v[196:199], v[104:107]
	v_mfma_f32_16x16x32_bf16 v[92:95], v[128:131], v[204:207], v[92:95]
	v_mfma_f32_16x16x32_bf16 v[88:91], v[152:155], v[204:207], v[88:91]
	v_mfma_f32_16x16x32_bf16 v[76:79], v[128:131], v[212:215], v[76:79]
	v_mfma_f32_16x16x32_bf16 v[72:75], v[152:155], v[212:215], v[72:75]
	v_mfma_f32_16x16x32_bf16 v[124:127], v[132:135], v[192:195], v[124:127]
	v_mfma_f32_16x16x32_bf16 v[120:123], v[164:167], v[192:195], v[120:123]
	v_mfma_f32_16x16x32_bf16 v[108:111], v[132:135], v[200:203], v[108:111]
	v_mfma_f32_16x16x32_bf16 v[104:107], v[164:167], v[200:203], v[104:107]
	v_mfma_f32_16x16x32_bf16 v[92:95], v[132:135], v[208:211], v[92:95]
	v_mfma_f32_16x16x32_bf16 v[88:91], v[164:167], v[208:211], v[88:91]
	v_mfma_f32_16x16x32_bf16 v[76:79], v[132:135], v[216:219], v[76:79]
	v_mfma_f32_16x16x32_bf16 v[72:75], v[164:167], v[216:219], v[72:75]
	v_mfma_f32_16x16x32_bf16 v[116:119], v[172:175], v[188:191], v[116:119]
	v_mfma_f32_16x16x32_bf16 v[112:115], v[180:183], v[188:191], v[112:115]
	v_mfma_f32_16x16x32_bf16 v[100:103], v[172:175], v[196:199], v[100:103]
	v_mfma_f32_16x16x32_bf16 v[96:99], v[180:183], v[196:199], v[96:99]
	v_mfma_f32_16x16x32_bf16 v[84:87], v[172:175], v[204:207], v[84:87]
	v_mfma_f32_16x16x32_bf16 v[80:83], v[180:183], v[204:207], v[80:83]
	v_mfma_f32_16x16x32_bf16 v[68:71], v[172:175], v[212:215], v[68:71]
	v_mfma_f32_16x16x32_bf16 v[64:67], v[180:183], v[212:215], v[64:67]
	v_mfma_f32_16x16x32_bf16 v[116:119], v[176:179], v[192:195], v[116:119]
	v_mfma_f32_16x16x32_bf16 v[112:115], v[184:187], v[192:195], v[112:115]
	v_mfma_f32_16x16x32_bf16 v[100:103], v[176:179], v[200:203], v[100:103]
	v_mfma_f32_16x16x32_bf16 v[96:99], v[184:187], v[200:203], v[96:99]
	v_mfma_f32_16x16x32_bf16 v[84:87], v[176:179], v[208:211], v[84:87]
	v_mfma_f32_16x16x32_bf16 v[80:83], v[184:187], v[208:211], v[80:83]
	v_mfma_f32_16x16x32_bf16 v[68:71], v[176:179], v[216:219], v[68:71]
	v_mfma_f32_16x16x32_bf16 v[64:67], v[184:187], v[216:219], v[64:67]
	s_barrier
	s_add_i32 s28, s49, s31
	v_lshl_add_u64 v[156:157], v[156:157], 0, s[10:11]
	s_mov_b32 m0, s28
	ds_read_b128 v[188:191], v163 offset:49152
	ds_read_b128 v[192:195], v163 offset:50176
	ds_read_b128 v[196:199], v163 offset:51200
	ds_read_b128 v[200:203], v163 offset:52224
	ds_read_b128 v[204:207], v163 offset:53248
	ds_read_b128 v[208:211], v163 offset:54272
	ds_read_b128 v[212:215], v163 offset:55296
	ds_read_b128 v[216:219], v163 offset:56320
	global_load_lds_dwordx4 v[156:157], off
	s_add_i32 m0, s28, 0x2000
	s_add_u32 s26, s26, 0x40080
	v_lshl_add_u64 v[156:157], v[168:169], 0, s[10:11]
	s_addc_u32 s27, s27, 0
	s_add_i32 s28, s50, s31
	global_load_lds_dwordx4 v[156:157], off
	s_mov_b32 m0, s28
	v_lshl_add_u64 v[156:157], s[26:27], 0, v[138:139]
	global_load_lds_dwordx4 v[156:157], off
	s_add_i32 m0, s28, 0x2000
	v_lshl_add_u64 v[156:157], s[26:27], 0, v[142:143]
	global_load_lds_dwordx4 v[156:157], off
	s_mov_b32 m0, s41
	v_lshl_add_u64 v[156:157], v[220:221], 0, s[10:11]
	global_load_lds_dwordx4 v[156:157], off
	s_mov_b32 m0, s42
	v_lshl_add_u64 v[156:157], v[222:223], 0, s[10:11]
	global_load_lds_dwordx4 v[156:157], off
	s_waitcnt vmcnt(8) lgkmcnt(0)
	s_barrier
	v_mfma_f32_16x16x32_bf16 v[60:63], v[128:131], v[188:191], v[60:63]
	v_mfma_f32_16x16x32_bf16 v[56:59], v[152:155], v[188:191], v[56:59]
	v_mfma_f32_16x16x32_bf16 v[44:47], v[128:131], v[196:199], v[44:47]
	v_mfma_f32_16x16x32_bf16 v[40:43], v[152:155], v[196:199], v[40:43]
	v_mfma_f32_16x16x32_bf16 v[28:31], v[128:131], v[204:207], v[28:31]
	v_mfma_f32_16x16x32_bf16 v[24:27], v[152:155], v[204:207], v[24:27]
	v_mfma_f32_16x16x32_bf16 v[12:15], v[128:131], v[212:215], v[12:15]
	v_mfma_f32_16x16x32_bf16 v[8:11], v[152:155], v[212:215], v[8:11]
	v_mfma_f32_16x16x32_bf16 v[60:63], v[132:135], v[192:195], v[60:63]
	v_mfma_f32_16x16x32_bf16 v[56:59], v[164:167], v[192:195], v[56:59]
	v_mfma_f32_16x16x32_bf16 v[44:47], v[132:135], v[200:203], v[44:47]
	v_mfma_f32_16x16x32_bf16 v[40:43], v[164:167], v[200:203], v[40:43]
	v_mfma_f32_16x16x32_bf16 v[28:31], v[132:135], v[208:211], v[28:31]
	v_mfma_f32_16x16x32_bf16 v[24:27], v[164:167], v[208:211], v[24:27]
	v_mfma_f32_16x16x32_bf16 v[12:15], v[132:135], v[216:219], v[12:15]
	v_mfma_f32_16x16x32_bf16 v[8:11], v[164:167], v[216:219], v[8:11]
	v_mfma_f32_16x16x32_bf16 v[52:55], v[172:175], v[188:191], v[52:55]
	v_mfma_f32_16x16x32_bf16 v[48:51], v[180:183], v[188:191], v[48:51]
	v_mfma_f32_16x16x32_bf16 v[36:39], v[172:175], v[196:199], v[36:39]
	v_mfma_f32_16x16x32_bf16 v[32:35], v[180:183], v[196:199], v[32:35]
	v_mfma_f32_16x16x32_bf16 v[20:23], v[172:175], v[204:207], v[20:23]
	v_mfma_f32_16x16x32_bf16 v[16:19], v[180:183], v[204:207], v[16:19]
	v_mfma_f32_16x16x32_bf16 v[4:7], v[172:175], v[212:215], v[4:7]
	v_mfma_f32_16x16x32_bf16 v[0:3], v[180:183], v[212:215], v[0:3]
	v_mfma_f32_16x16x32_bf16 v[52:55], v[176:179], v[192:195], v[52:55]
	v_mfma_f32_16x16x32_bf16 v[48:51], v[184:187], v[192:195], v[48:51]
	v_mfma_f32_16x16x32_bf16 v[36:39], v[176:179], v[200:203], v[36:39]
	v_mfma_f32_16x16x32_bf16 v[32:35], v[184:187], v[200:203], v[32:35]
	v_mfma_f32_16x16x32_bf16 v[20:23], v[176:179], v[208:211], v[20:23]
	v_mfma_f32_16x16x32_bf16 v[16:19], v[184:187], v[208:211], v[16:19]
	v_mfma_f32_16x16x32_bf16 v[4:7], v[176:179], v[216:219], v[4:7]
	v_mfma_f32_16x16x32_bf16 v[0:3], v[184:187], v[216:219], v[0:3]
	s_barrier
	s_add_i32 s47, s47, 2
	s_add_u32 s2, s2, 0x100
	s_addc_u32 s3, s3, 0
	s_add_u32 s33, s33, 0x100
	s_addc_u32 s46, s46, 0
	s_cmp_gt_u32 s47, 13
	s_cbranch_scc0 .LBB0_124
	s_and_b64 vcc, exec, s[12:13]
	s_cbranch_vccz .LBB0_127
	s_barrier

.Lpeel457_mid:
	s_add_i32 s47, 0, 0x18000
	v_add_u32_e32 v144, s47, v146
	s_add_i32 s48, 0, 0x1c000
	ds_read_b128 v[152:155], v144
	ds_read_b128 v[156:159], v144 offset:1024
	ds_read_b128 v[160:163], v144 offset:2048
	ds_read_b128 v[164:167], v144 offset:3072
	v_add_u32_e32 v144, s48, v146
	ds_read_b128 v[172:175], v144
	ds_read_b128 v[176:179], v144 offset:1024
	ds_read_b128 v[180:183], v144 offset:2048
	ds_read_b128 v[184:187], v144 offset:3072
	s_add_u32 s24, s24, 0x40000
	s_addc_u32 s25, s25, 0
	s_mov_b32 m0, s30
	v_lshl_add_u64 v[226:227], s[24:25], 0, v[128:129]
	ds_read_b128 v[188:191], v150 offset:32768
	ds_read_b128 v[192:195], v150 offset:33792
	ds_read_b128 v[196:199], v150 offset:34816
	ds_read_b128 v[200:203], v150 offset:35840
	ds_read_b128 v[204:207], v150 offset:36864
	ds_read_b128 v[208:211], v150 offset:37888
	ds_read_b128 v[212:215], v150 offset:38912
	ds_read_b128 v[216:219], v150 offset:39936
	global_load_lds_dwordx4 v[226:227], off
	s_mov_b32 m0, s31
	v_lshl_add_u64 v[226:227], s[24:25], 0, v[132:133]
	global_load_lds_dwordx4 v[226:227], off
	s_waitcnt vmcnt(8) lgkmcnt(0)
	s_barrier
	v_mfma_f32_16x16x32_bf16 v[124:127], v[152:155], v[188:191], v[124:127]
	v_mfma_f32_16x16x32_bf16 v[120:123], v[160:163], v[188:191], v[120:123]
	v_mfma_f32_16x16x32_bf16 v[116:119], v[152:155], v[196:199], v[116:119]
	v_mfma_f32_16x16x32_bf16 v[108:111], v[160:163], v[196:199], v[108:111]
	v_mfma_f32_16x16x32_bf16 v[100:103], v[152:155], v[204:207], v[100:103]
	v_mfma_f32_16x16x32_bf16 v[92:95], v[160:163], v[204:207], v[92:95]
	v_mfma_f32_16x16x32_bf16 v[84:87], v[152:155], v[212:215], v[84:87]
	v_mfma_f32_16x16x32_bf16 v[76:79], v[160:163], v[212:215], v[76:79]
	v_mfma_f32_16x16x32_bf16 v[124:127], v[156:159], v[192:195], v[124:127]
	v_mfma_f32_16x16x32_bf16 v[120:123], v[164:167], v[192:195], v[120:123]
	v_mfma_f32_16x16x32_bf16 v[116:119], v[156:159], v[200:203], v[116:119]
	v_mfma_f32_16x16x32_bf16 v[108:111], v[164:167], v[200:203], v[108:111]
	v_mfma_f32_16x16x32_bf16 v[100:103], v[156:159], v[208:211], v[100:103]
	v_mfma_f32_16x16x32_bf16 v[92:95], v[164:167], v[208:211], v[92:95]
	v_mfma_f32_16x16x32_bf16 v[84:87], v[156:159], v[216:219], v[84:87]
	v_mfma_f32_16x16x32_bf16 v[76:79], v[164:167], v[216:219], v[76:79]
	v_mfma_f32_16x16x32_bf16 v[112:115], v[172:175], v[188:191], v[112:115]
	v_mfma_f32_16x16x32_bf16 v[104:107], v[180:183], v[188:191], v[104:107]
	v_mfma_f32_16x16x32_bf16 v[96:99], v[172:175], v[196:199], v[96:99]
	v_mfma_f32_16x16x32_bf16 v[88:91], v[180:183], v[196:199], v[88:91]
	v_mfma_f32_16x16x32_bf16 v[80:83], v[172:175], v[204:207], v[80:83]
	v_mfma_f32_16x16x32_bf16 v[72:75], v[180:183], v[204:207], v[72:75]
	v_mfma_f32_16x16x32_bf16 v[68:71], v[172:175], v[212:215], v[68:71]
	v_mfma_f32_16x16x32_bf16 v[64:67], v[180:183], v[212:215], v[64:67]
	v_mfma_f32_16x16x32_bf16 v[112:115], v[176:179], v[192:195], v[112:115]
	v_mfma_f32_16x16x32_bf16 v[104:107], v[184:187], v[192:195], v[104:107]
	v_mfma_f32_16x16x32_bf16 v[96:99], v[176:179], v[200:203], v[96:99]
	v_mfma_f32_16x16x32_bf16 v[88:91], v[184:187], v[200:203], v[88:91]
	v_mfma_f32_16x16x32_bf16 v[80:83], v[176:179], v[208:211], v[80:83]
	v_mfma_f32_16x16x32_bf16 v[72:75], v[184:187], v[208:211], v[72:75]
	v_mfma_f32_16x16x32_bf16 v[68:71], v[176:179], v[216:219], v[68:71]
	v_mfma_f32_16x16x32_bf16 v[64:67], v[184:187], v[216:219], v[64:67]
	s_barrier
	s_add_i32 s24, s47, s26
	v_lshl_add_u64 v[168:169], v[168:169], 0, s[6:7]
	s_mov_b32 m0, s24
	ds_read_b128 v[188:191], v150 offset:49152
	ds_read_b128 v[192:195], v150 offset:50176
	ds_read_b128 v[196:199], v150 offset:51200
	ds_read_b128 v[200:203], v150 offset:52224
	ds_read_b128 v[204:207], v150 offset:53248
	ds_read_b128 v[208:211], v150 offset:54272
	ds_read_b128 v[212:215], v150 offset:55296
	ds_read_b128 v[216:219], v150 offset:56320
	global_load_lds_dwordx4 v[168:169], off
	s_add_i32 m0, s24, 0x2000
	s_add_u32 s22, s22, 0x40080
	v_lshl_add_u64 v[168:169], v[220:221], 0, s[6:7]
	s_addc_u32 s23, s23, 0
	s_add_i32 s24, s48, s26
	global_load_lds_dwordx4 v[168:169], off
	s_mov_b32 m0, s24
	v_lshl_add_u64 v[168:169], s[22:23], 0, v[130:131]
	global_load_lds_dwordx4 v[168:169], off
	s_add_i32 m0, s24, 0x2000
	v_lshl_add_u64 v[168:169], s[22:23], 0, v[134:135]
	global_load_lds_dwordx4 v[168:169], off
	s_mov_b32 m0, s35
	v_lshl_add_u64 v[168:169], v[222:223], 0, s[6:7]
	global_load_lds_dwordx4 v[168:169], off
	s_mov_b32 m0, s36
	v_lshl_add_u64 v[168:169], v[224:225], 0, s[6:7]
	global_load_lds_dwordx4 v[168:169], off
	s_waitcnt vmcnt(8) lgkmcnt(0)
	s_barrier
	v_mfma_f32_16x16x32_bf16 v[60:63], v[152:155], v[188:191], v[60:63]
	v_mfma_f32_16x16x32_bf16 v[56:59], v[160:163], v[188:191], v[56:59]
	v_mfma_f32_16x16x32_bf16 v[52:55], v[152:155], v[196:199], v[52:55]
	v_mfma_f32_16x16x32_bf16 v[44:47], v[160:163], v[196:199], v[44:47]
	v_mfma_f32_16x16x32_bf16 v[36:39], v[152:155], v[204:207], v[36:39]
	v_mfma_f32_16x16x32_bf16 v[28:31], v[160:163], v[204:207], v[28:31]
	v_mfma_f32_16x16x32_bf16 v[20:23], v[152:155], v[212:215], v[20:23]
	v_mfma_f32_16x16x32_bf16 v[12:15], v[160:163], v[212:215], v[12:15]
	v_mfma_f32_16x16x32_bf16 v[60:63], v[156:159], v[192:195], v[60:63]
	v_mfma_f32_16x16x32_bf16 v[56:59], v[164:167], v[192:195], v[56:59]
	v_mfma_f32_16x16x32_bf16 v[52:55], v[156:159], v[200:203], v[52:55]
	v_mfma_f32_16x16x32_bf16 v[44:47], v[164:167], v[200:203], v[44:47]
	v_mfma_f32_16x16x32_bf16 v[36:39], v[156:159], v[208:211], v[36:39]
	v_mfma_f32_16x16x32_bf16 v[28:31], v[164:167], v[208:211], v[28:31]
	v_mfma_f32_16x16x32_bf16 v[20:23], v[156:159], v[216:219], v[20:23]
	v_mfma_f32_16x16x32_bf16 v[12:15], v[164:167], v[216:219], v[12:15]
	v_mfma_f32_16x16x32_bf16 v[48:51], v[172:175], v[188:191], v[48:51]
	v_mfma_f32_16x16x32_bf16 v[40:43], v[180:183], v[188:191], v[40:43]
	v_mfma_f32_16x16x32_bf16 v[32:35], v[172:175], v[196:199], v[32:35]
	v_mfma_f32_16x16x32_bf16 v[24:27], v[180:183], v[196:199], v[24:27]
	v_mfma_f32_16x16x32_bf16 v[16:19], v[172:175], v[204:207], v[16:19]
	v_mfma_f32_16x16x32_bf16 v[8:11], v[180:183], v[204:207], v[8:11]
	v_mfma_f32_16x16x32_bf16 v[4:7], v[172:175], v[212:215], v[4:7]
	v_mfma_f32_16x16x32_bf16 v[0:3], v[180:183], v[212:215], v[0:3]
	v_mfma_f32_16x16x32_bf16 v[48:51], v[176:179], v[192:195], v[48:51]
	v_mfma_f32_16x16x32_bf16 v[40:43], v[184:187], v[192:195], v[40:43]
	v_mfma_f32_16x16x32_bf16 v[32:35], v[176:179], v[200:203], v[32:35]
	v_mfma_f32_16x16x32_bf16 v[24:27], v[184:187], v[200:203], v[24:27]
	v_mfma_f32_16x16x32_bf16 v[16:19], v[176:179], v[208:211], v[16:19]
	v_mfma_f32_16x16x32_bf16 v[8:11], v[184:187], v[208:211], v[8:11]
	v_mfma_f32_16x16x32_bf16 v[4:7], v[176:179], v[216:219], v[4:7]
	v_mfma_f32_16x16x32_bf16 v[0:3], v[184:187], v[216:219], v[0:3]
	s_barrier
	s_add_i32 s46, s46, 2
	s_add_u32 s20, s20, 0x100
	s_addc_u32 s21, s21, 0
	s_add_u32 s44, s44, 0x100
	s_addc_u32 s45, s45, 0
	s_cmp_gt_u32 s46, 13
	s_cbranch_scc0 .LBB0_457
	s_and_b64 vcc, exec, s[8:9]
	s_cbranch_vccz .LBB0_460
	s_barrier

.Lpeel646_mid:
	s_add_i32 s55, 0, 0x18000
	v_add_u32_e32 v130, s55, v154
	s_add_i32 s56, 0, 0x1c000
	ds_read_b128 v[134:137], v130
	ds_read_b128 v[160:163], v130 offset:1024
	ds_read_b128 v[164:167], v130 offset:2048
	ds_read_b128 v[184:187], v130 offset:3072
	v_add_u32_e32 v130, s56, v154
	ds_read_b128 v[188:191], v130
	ds_read_b128 v[192:195], v130 offset:1024
	ds_read_b128 v[196:199], v130 offset:2048
	ds_read_b128 v[200:203], v130 offset:3072
	s_add_u32 s34, s34, 0x40000
	s_addc_u32 s35, s35, 0
	s_mov_b32 m0, s43
	v_lshl_add_u64 v[240:241], s[34:35], 0, v[140:141]
	ds_read_b128 v[204:207], v158 offset:32768
	ds_read_b128 v[208:211], v158 offset:33792
	ds_read_b128 v[212:215], v158 offset:34816
	ds_read_b128 v[216:219], v158 offset:35840
	ds_read_b128 v[220:223], v158 offset:36864
	ds_read_b128 v[224:227], v158 offset:37888
	ds_read_b128 v[228:231], v158 offset:38912
	ds_read_b128 v[232:235], v158 offset:39936
	global_load_lds_dwordx4 v[240:241], off
	s_mov_b32 m0, s44
	v_lshl_add_u64 v[240:241], s[34:35], 0, v[144:145]
	global_load_lds_dwordx4 v[240:241], off
	s_waitcnt vmcnt(8) lgkmcnt(0)
	s_barrier
	v_mfma_f32_16x16x32_bf16 v[124:127], v[134:137], v[204:207], v[124:127]
	v_mfma_f32_16x16x32_bf16 v[120:123], v[164:167], v[204:207], v[120:123]
	v_mfma_f32_16x16x32_bf16 v[108:111], v[134:137], v[212:215], v[108:111]
	v_mfma_f32_16x16x32_bf16 v[104:107], v[164:167], v[212:215], v[104:107]
	v_mfma_f32_16x16x32_bf16 v[92:95], v[134:137], v[220:223], v[92:95]
	v_mfma_f32_16x16x32_bf16 v[88:91], v[164:167], v[220:223], v[88:91]
	v_mfma_f32_16x16x32_bf16 v[76:79], v[134:137], v[228:231], v[76:79]
	v_mfma_f32_16x16x32_bf16 v[72:75], v[164:167], v[228:231], v[72:75]
	v_mfma_f32_16x16x32_bf16 v[124:127], v[160:163], v[208:211], v[124:127]
	v_mfma_f32_16x16x32_bf16 v[120:123], v[184:187], v[208:211], v[120:123]
	v_mfma_f32_16x16x32_bf16 v[108:111], v[160:163], v[216:219], v[108:111]
	v_mfma_f32_16x16x32_bf16 v[104:107], v[184:187], v[216:219], v[104:107]
	v_mfma_f32_16x16x32_bf16 v[92:95], v[160:163], v[224:227], v[92:95]
	v_mfma_f32_16x16x32_bf16 v[88:91], v[184:187], v[224:227], v[88:91]
	v_mfma_f32_16x16x32_bf16 v[76:79], v[160:163], v[232:235], v[76:79]
	v_mfma_f32_16x16x32_bf16 v[72:75], v[184:187], v[232:235], v[72:75]
	v_mfma_f32_16x16x32_bf16 v[116:119], v[188:191], v[204:207], v[116:119]
	v_mfma_f32_16x16x32_bf16 v[112:115], v[196:199], v[204:207], v[112:115]
	v_mfma_f32_16x16x32_bf16 v[100:103], v[188:191], v[212:215], v[100:103]
	v_mfma_f32_16x16x32_bf16 v[96:99], v[196:199], v[212:215], v[96:99]
	v_mfma_f32_16x16x32_bf16 v[84:87], v[188:191], v[220:223], v[84:87]
	v_mfma_f32_16x16x32_bf16 v[80:83], v[196:199], v[220:223], v[80:83]
	v_mfma_f32_16x16x32_bf16 v[68:71], v[188:191], v[228:231], v[68:71]
	v_mfma_f32_16x16x32_bf16 v[64:67], v[196:199], v[228:231], v[64:67]
	v_mfma_f32_16x16x32_bf16 v[116:119], v[192:195], v[208:211], v[116:119]
	v_mfma_f32_16x16x32_bf16 v[112:115], v[200:203], v[208:211], v[112:115]
	v_mfma_f32_16x16x32_bf16 v[100:103], v[192:195], v[216:219], v[100:103]
	v_mfma_f32_16x16x32_bf16 v[96:99], v[200:203], v[216:219], v[96:99]
	v_mfma_f32_16x16x32_bf16 v[84:87], v[192:195], v[224:227], v[84:87]
	v_mfma_f32_16x16x32_bf16 v[80:83], v[200:203], v[224:227], v[80:83]
	v_mfma_f32_16x16x32_bf16 v[68:71], v[192:195], v[232:235], v[68:71]
	v_mfma_f32_16x16x32_bf16 v[64:67], v[200:203], v[232:235], v[64:67]
	s_barrier
	s_add_i32 s34, s55, s41
	v_lshl_add_u64 v[138:139], v[138:139], 0, s[12:13]
	s_mov_b32 m0, s34
	ds_read_b128 v[204:207], v158 offset:49152
	ds_read_b128 v[208:211], v158 offset:50176
	ds_read_b128 v[212:215], v158 offset:51200
	ds_read_b128 v[216:219], v158 offset:52224
	ds_read_b128 v[220:223], v158 offset:53248
	ds_read_b128 v[224:227], v158 offset:54272
	ds_read_b128 v[228:231], v158 offset:55296
	ds_read_b128 v[232:235], v158 offset:56320
	global_load_lds_dwordx4 v[138:139], off
	s_add_i32 m0, s34, 0x2000
	s_add_u32 s28, s28, 0x40080
	v_lshl_add_u64 v[138:139], v[168:169], 0, s[12:13]
	s_addc_u32 s29, s29, 0
	s_add_i32 s34, s56, s41
	global_load_lds_dwordx4 v[138:139], off
	s_mov_b32 m0, s34
	v_lshl_add_u64 v[138:139], s[28:29], 0, v[142:143]
	global_load_lds_dwordx4 v[138:139], off
	s_add_i32 m0, s34, 0x2000
	v_lshl_add_u64 v[138:139], s[28:29], 0, v[146:147]
	global_load_lds_dwordx4 v[138:139], off
	s_mov_b32 m0, s45
	v_lshl_add_u64 v[138:139], v[236:237], 0, s[12:13]
	global_load_lds_dwordx4 v[138:139], off
	s_mov_b32 m0, s46
	v_lshl_add_u64 v[138:139], v[238:239], 0, s[12:13]
	global_load_lds_dwordx4 v[138:139], off
	s_waitcnt vmcnt(8) lgkmcnt(0)
	s_barrier
	v_mfma_f32_16x16x32_bf16 v[60:63], v[134:137], v[204:207], v[60:63]
	v_mfma_f32_16x16x32_bf16 v[56:59], v[164:167], v[204:207], v[56:59]
	v_mfma_f32_16x16x32_bf16 v[44:47], v[134:137], v[212:215], v[44:47]
	v_mfma_f32_16x16x32_bf16 v[40:43], v[164:167], v[212:215], v[40:43]
	v_mfma_f32_16x16x32_bf16 v[28:31], v[134:137], v[220:223], v[28:31]
	v_mfma_f32_16x16x32_bf16 v[24:27], v[164:167], v[220:223], v[24:27]
	v_mfma_f32_16x16x32_bf16 v[12:15], v[134:137], v[228:231], v[12:15]
	v_mfma_f32_16x16x32_bf16 v[8:11], v[164:167], v[228:231], v[8:11]
	v_mfma_f32_16x16x32_bf16 v[60:63], v[160:163], v[208:211], v[60:63]
	v_mfma_f32_16x16x32_bf16 v[56:59], v[184:187], v[208:211], v[56:59]
	v_mfma_f32_16x16x32_bf16 v[44:47], v[160:163], v[216:219], v[44:47]
	v_mfma_f32_16x16x32_bf16 v[40:43], v[184:187], v[216:219], v[40:43]
	v_mfma_f32_16x16x32_bf16 v[28:31], v[160:163], v[224:227], v[28:31]
	v_mfma_f32_16x16x32_bf16 v[24:27], v[184:187], v[224:227], v[24:27]
	v_mfma_f32_16x16x32_bf16 v[12:15], v[160:163], v[232:235], v[12:15]
	v_mfma_f32_16x16x32_bf16 v[8:11], v[184:187], v[232:235], v[8:11]
	v_mfma_f32_16x16x32_bf16 v[52:55], v[188:191], v[204:207], v[52:55]
	v_mfma_f32_16x16x32_bf16 v[48:51], v[196:199], v[204:207], v[48:51]
	v_mfma_f32_16x16x32_bf16 v[36:39], v[188:191], v[212:215], v[36:39]
	v_mfma_f32_16x16x32_bf16 v[32:35], v[196:199], v[212:215], v[32:35]
	v_mfma_f32_16x16x32_bf16 v[20:23], v[188:191], v[220:223], v[20:23]
	v_mfma_f32_16x16x32_bf16 v[16:19], v[196:199], v[220:223], v[16:19]
	v_mfma_f32_16x16x32_bf16 v[4:7], v[188:191], v[228:231], v[4:7]
	v_mfma_f32_16x16x32_bf16 v[0:3], v[196:199], v[228:231], v[0:3]
	v_mfma_f32_16x16x32_bf16 v[52:55], v[192:195], v[208:211], v[52:55]
	v_mfma_f32_16x16x32_bf16 v[48:51], v[200:203], v[208:211], v[48:51]
	v_mfma_f32_16x16x32_bf16 v[36:39], v[192:195], v[216:219], v[36:39]
	v_mfma_f32_16x16x32_bf16 v[32:35], v[200:203], v[216:219], v[32:35]
	v_mfma_f32_16x16x32_bf16 v[20:23], v[192:195], v[224:227], v[20:23]
	v_mfma_f32_16x16x32_bf16 v[16:19], v[200:203], v[224:227], v[16:19]
	v_mfma_f32_16x16x32_bf16 v[4:7], v[192:195], v[232:235], v[4:7]
	v_mfma_f32_16x16x32_bf16 v[0:3], v[200:203], v[232:235], v[0:3]
	s_barrier
	s_add_i32 s54, s54, 2
	s_add_u32 s26, s26, 0x100
	s_addc_u32 s27, s27, 0
	s_add_u32 s52, s52, 0x100
	s_addc_u32 s53, s53, 0
	s_cmp_gt_u32 s54, 13
	s_cbranch_scc0 .LBB0_646
	s_and_b64 vcc, exec, s[14:15]
	s_cbranch_vccz .LBB0_649
	s_barrier

.Lpeel666_mid:
	s_add_i32 s55, 0, 0x18000
	s_add_i32 s56, 0, 0x1c000
	v_add_u32_e32 v164, s55, v185
	v_add_u32_e32 v202, s56, v185
	ds_read_b128 v[128:131], v164
	ds_read_b128 v[132:135], v164 offset:1024
	ds_read_b128 v[136:139], v164 offset:2048
	ds_read_b128 v[164:167], v164 offset:3072
	ds_read_b128 v[190:193], v202
	ds_read_b128 v[194:197], v202 offset:1024
	ds_read_b128 v[198:201], v202 offset:2048
	ds_read_b128 v[202:205], v202 offset:3072
	s_add_u32 s34, s34, 0x20000
	s_addc_u32 s35, s35, 0
	s_mov_b32 m0, s42
	v_lshl_add_u64 v[244:245], s[34:35], 0, v[148:149]
	ds_read_b128 v[206:209], v189 offset:32768
	ds_read_b128 v[210:213], v189 offset:33792
	ds_read_b128 v[214:217], v189 offset:34816
	ds_read_b128 v[218:221], v189 offset:35840
	ds_read_b128 v[222:225], v189 offset:36864
	ds_read_b128 v[226:229], v189 offset:37888
	ds_read_b128 v[230:233], v189 offset:38912
	ds_read_b128 v[234:237], v189 offset:39936
	global_load_lds_dwordx4 v[244:245], off
	s_mov_b32 m0, s43
	v_lshl_add_u64 v[244:245], s[34:35], 0, v[152:153]
	global_load_lds_dwordx4 v[244:245], off
	s_waitcnt vmcnt(8) lgkmcnt(0)
	s_barrier
	v_mfma_f32_16x16x32_bf16 v[124:127], v[128:131], v[206:209], v[124:127]
	v_mfma_f32_16x16x32_bf16 v[120:123], v[136:139], v[206:209], v[120:123]
	v_mfma_f32_16x16x32_bf16 v[112:115], v[128:131], v[214:217], v[112:115]
	v_mfma_f32_16x16x32_bf16 v[104:107], v[136:139], v[214:217], v[104:107]
	v_mfma_f32_16x16x32_bf16 v[92:95], v[128:131], v[222:225], v[92:95]
	v_mfma_f32_16x16x32_bf16 v[88:91], v[136:139], v[222:225], v[88:91]
	v_mfma_f32_16x16x32_bf16 v[76:79], v[128:131], v[230:233], v[76:79]
	v_mfma_f32_16x16x32_bf16 v[72:75], v[136:139], v[230:233], v[72:75]
	v_mfma_f32_16x16x32_bf16 v[124:127], v[132:135], v[210:213], v[124:127]
	v_mfma_f32_16x16x32_bf16 v[120:123], v[164:167], v[210:213], v[120:123]
	v_mfma_f32_16x16x32_bf16 v[112:115], v[132:135], v[218:221], v[112:115]
	v_mfma_f32_16x16x32_bf16 v[104:107], v[164:167], v[218:221], v[104:107]
	v_mfma_f32_16x16x32_bf16 v[92:95], v[132:135], v[226:229], v[92:95]
	v_mfma_f32_16x16x32_bf16 v[88:91], v[164:167], v[226:229], v[88:91]
	v_mfma_f32_16x16x32_bf16 v[76:79], v[132:135], v[234:237], v[76:79]
	v_mfma_f32_16x16x32_bf16 v[72:75], v[164:167], v[234:237], v[72:75]
	v_mfma_f32_16x16x32_bf16 v[116:119], v[190:193], v[206:209], v[116:119]
	v_mfma_f32_16x16x32_bf16 v[108:111], v[198:201], v[206:209], v[108:111]
	v_mfma_f32_16x16x32_bf16 v[100:103], v[190:193], v[214:217], v[100:103]
	v_mfma_f32_16x16x32_bf16 v[96:99], v[198:201], v[214:217], v[96:99]
	v_mfma_f32_16x16x32_bf16 v[84:87], v[190:193], v[222:225], v[84:87]
	v_mfma_f32_16x16x32_bf16 v[80:83], v[198:201], v[222:225], v[80:83]
	v_mfma_f32_16x16x32_bf16 v[68:71], v[190:193], v[230:233], v[68:71]
	v_mfma_f32_16x16x32_bf16 v[64:67], v[198:201], v[230:233], v[64:67]
	v_mfma_f32_16x16x32_bf16 v[116:119], v[194:197], v[210:213], v[116:119]
	v_mfma_f32_16x16x32_bf16 v[108:111], v[202:205], v[210:213], v[108:111]
	v_mfma_f32_16x16x32_bf16 v[100:103], v[194:197], v[218:221], v[100:103]
	v_mfma_f32_16x16x32_bf16 v[96:99], v[202:205], v[218:221], v[96:99]
	v_mfma_f32_16x16x32_bf16 v[84:87], v[194:197], v[226:229], v[84:87]
	v_mfma_f32_16x16x32_bf16 v[80:83], v[202:205], v[226:229], v[80:83]
	v_mfma_f32_16x16x32_bf16 v[68:71], v[194:197], v[234:237], v[68:71]
	v_mfma_f32_16x16x32_bf16 v[64:67], v[202:205], v[234:237], v[64:67]
	s_barrier
	s_add_i32 s34, s55, s40
	v_lshl_add_u64 v[168:169], v[168:169], 0, s[12:13]
	s_mov_b32 m0, s34
	ds_read_b128 v[206:209], v189 offset:49152
	ds_read_b128 v[210:213], v189 offset:50176
	ds_read_b128 v[214:217], v189 offset:51200
	ds_read_b128 v[218:221], v189 offset:52224
	ds_read_b128 v[222:225], v189 offset:53248
	ds_read_b128 v[226:229], v189 offset:54272
	ds_read_b128 v[230:233], v189 offset:55296
	ds_read_b128 v[234:237], v189 offset:56320
	global_load_lds_dwordx4 v[168:169], off
	s_add_i32 m0, s34, 0x2000
	s_add_u32 s28, s28, 0x20080
	v_lshl_add_u64 v[168:169], v[238:239], 0, s[12:13]
	s_addc_u32 s29, s29, 0
	s_add_i32 s34, s56, s40
	global_load_lds_dwordx4 v[168:169], off
	s_mov_b32 m0, s34
	v_lshl_add_u64 v[168:169], s[28:29], 0, v[150:151]
	global_load_lds_dwordx4 v[168:169], off
	s_add_i32 m0, s34, 0x2000
	v_lshl_add_u64 v[168:169], s[28:29], 0, v[154:155]
	global_load_lds_dwordx4 v[168:169], off
	s_mov_b32 m0, s45
	v_lshl_add_u64 v[168:169], v[240:241], 0, s[12:13]
	global_load_lds_dwordx4 v[168:169], off
	s_mov_b32 m0, s46
	v_lshl_add_u64 v[168:169], v[242:243], 0, s[12:13]
	global_load_lds_dwordx4 v[168:169], off
	s_waitcnt vmcnt(8) lgkmcnt(0)
	s_barrier
	v_mfma_f32_16x16x32_bf16 v[60:63], v[128:131], v[206:209], v[60:63]
	v_mfma_f32_16x16x32_bf16 v[56:59], v[136:139], v[206:209], v[56:59]
	v_mfma_f32_16x16x32_bf16 v[44:47], v[128:131], v[214:217], v[44:47]
	v_mfma_f32_16x16x32_bf16 v[40:43], v[136:139], v[214:217], v[40:43]
	v_mfma_f32_16x16x32_bf16 v[36:39], v[128:131], v[222:225], v[36:39]
	v_mfma_f32_16x16x32_bf16 v[32:35], v[136:139], v[222:225], v[32:35]
	v_mfma_f32_16x16x32_bf16 v[20:23], v[128:131], v[230:233], v[20:23]
	v_mfma_f32_16x16x32_bf16 v[16:19], v[136:139], v[230:233], v[16:19]
	v_mfma_f32_16x16x32_bf16 v[60:63], v[132:135], v[210:213], v[60:63]
	v_mfma_f32_16x16x32_bf16 v[56:59], v[164:167], v[210:213], v[56:59]
	v_mfma_f32_16x16x32_bf16 v[44:47], v[132:135], v[218:221], v[44:47]
	v_mfma_f32_16x16x32_bf16 v[40:43], v[164:167], v[218:221], v[40:43]
	v_mfma_f32_16x16x32_bf16 v[36:39], v[132:135], v[226:229], v[36:39]
	v_mfma_f32_16x16x32_bf16 v[32:35], v[164:167], v[226:229], v[32:35]
	v_mfma_f32_16x16x32_bf16 v[20:23], v[132:135], v[234:237], v[20:23]
	v_mfma_f32_16x16x32_bf16 v[16:19], v[164:167], v[234:237], v[16:19]
	v_mfma_f32_16x16x32_bf16 v[52:55], v[190:193], v[206:209], v[52:55]
	v_mfma_f32_16x16x32_bf16 v[48:51], v[198:201], v[206:209], v[48:51]
	v_mfma_f32_16x16x32_bf16 v[28:31], v[190:193], v[214:217], v[28:31]
	v_mfma_f32_16x16x32_bf16 v[24:27], v[198:201], v[214:217], v[24:27]
	v_mfma_f32_16x16x32_bf16 v[12:15], v[190:193], v[222:225], v[12:15]
	v_mfma_f32_16x16x32_bf16 v[8:11], v[198:201], v[222:225], v[8:11]
	v_mfma_f32_16x16x32_bf16 v[4:7], v[190:193], v[230:233], v[4:7]
	v_mfma_f32_16x16x32_bf16 v[0:3], v[198:201], v[230:233], v[0:3]
	v_mfma_f32_16x16x32_bf16 v[52:55], v[194:197], v[210:213], v[52:55]
	v_mfma_f32_16x16x32_bf16 v[48:51], v[202:205], v[210:213], v[48:51]
	v_mfma_f32_16x16x32_bf16 v[28:31], v[194:197], v[218:221], v[28:31]
	v_mfma_f32_16x16x32_bf16 v[24:27], v[202:205], v[218:221], v[24:27]
	v_mfma_f32_16x16x32_bf16 v[12:15], v[194:197], v[226:229], v[12:15]
	v_mfma_f32_16x16x32_bf16 v[8:11], v[202:205], v[226:229], v[8:11]
	v_mfma_f32_16x16x32_bf16 v[4:7], v[194:197], v[234:237], v[4:7]
	v_mfma_f32_16x16x32_bf16 v[0:3], v[202:205], v[234:237], v[0:3]
	s_barrier
	s_add_i32 s54, s54, 2
	s_add_u32 s26, s26, 0x100
	s_addc_u32 s27, s27, 0
	s_add_u32 s52, s52, 0x100
	s_addc_u32 s53, s53, 0
	s_cmp_gt_u32 s54, 5
	s_cbranch_scc0 .LBB0_666
	s_and_b64 vcc, exec, s[14:15]
	s_cbranch_vccz .LBB0_669
	s_barrier

.Lpeel686_mid:
	s_add_i32 s54, 0, 0x18000
	s_add_i32 s55, 0, 0x1c000
	v_add_u32_e32 v164, s54, v151
	v_add_u32_e32 v179, s55, v151
	ds_read_b128 v[136:139], v164
	ds_read_b128 v[156:159], v164 offset:1024
	ds_read_b128 v[160:163], v164 offset:2048
	ds_read_b128 v[164:167], v164 offset:3072
	ds_read_b128 v[180:183], v179
	ds_read_b128 v[184:187], v179 offset:1024
	ds_read_b128 v[188:191], v179 offset:2048
	ds_read_b128 v[192:195], v179 offset:3072
	s_add_u32 s36, s36, 0x40000
	s_addc_u32 s37, s37, 0
	s_mov_b32 m0, s41
	v_lshl_add_u64 v[232:233], s[36:37], 0, v[140:141]
	ds_read_b128 v[196:199], v155 offset:32768
	ds_read_b128 v[200:203], v155 offset:33792
	ds_read_b128 v[204:207], v155 offset:34816
	ds_read_b128 v[208:211], v155 offset:35840
	ds_read_b128 v[212:215], v155 offset:36864
	ds_read_b128 v[216:219], v155 offset:37888
	ds_read_b128 v[220:223], v155 offset:38912
	ds_read_b128 v[224:227], v155 offset:39936
	global_load_lds_dwordx4 v[232:233], off
	s_mov_b32 m0, s42
	v_lshl_add_u64 v[232:233], s[36:37], 0, v[144:145]
	global_load_lds_dwordx4 v[232:233], off
	s_waitcnt vmcnt(8) lgkmcnt(0)
	s_barrier
	v_mfma_f32_16x16x32_bf16 v[124:127], v[136:139], v[196:199], v[124:127]
	v_mfma_f32_16x16x32_bf16 v[120:123], v[160:163], v[196:199], v[120:123]
	v_mfma_f32_16x16x32_bf16 v[108:111], v[136:139], v[204:207], v[108:111]
	v_mfma_f32_16x16x32_bf16 v[104:107], v[160:163], v[204:207], v[104:107]
	v_mfma_f32_16x16x32_bf16 v[92:95], v[136:139], v[212:215], v[92:95]
	v_mfma_f32_16x16x32_bf16 v[88:91], v[160:163], v[212:215], v[88:91]
	v_mfma_f32_16x16x32_bf16 v[76:79], v[136:139], v[220:223], v[76:79]
	v_mfma_f32_16x16x32_bf16 v[72:75], v[160:163], v[220:223], v[72:75]
	v_mfma_f32_16x16x32_bf16 v[124:127], v[156:159], v[200:203], v[124:127]
	v_mfma_f32_16x16x32_bf16 v[120:123], v[164:167], v[200:203], v[120:123]
	v_mfma_f32_16x16x32_bf16 v[108:111], v[156:159], v[208:211], v[108:111]
	v_mfma_f32_16x16x32_bf16 v[104:107], v[164:167], v[208:211], v[104:107]
	v_mfma_f32_16x16x32_bf16 v[92:95], v[156:159], v[216:219], v[92:95]
	v_mfma_f32_16x16x32_bf16 v[88:91], v[164:167], v[216:219], v[88:91]
	v_mfma_f32_16x16x32_bf16 v[76:79], v[156:159], v[224:227], v[76:79]
	v_mfma_f32_16x16x32_bf16 v[72:75], v[164:167], v[224:227], v[72:75]
	v_mfma_f32_16x16x32_bf16 v[116:119], v[180:183], v[196:199], v[116:119]
	v_mfma_f32_16x16x32_bf16 v[112:115], v[188:191], v[196:199], v[112:115]
	v_mfma_f32_16x16x32_bf16 v[100:103], v[180:183], v[204:207], v[100:103]
	v_mfma_f32_16x16x32_bf16 v[96:99], v[188:191], v[204:207], v[96:99]
	v_mfma_f32_16x16x32_bf16 v[84:87], v[180:183], v[212:215], v[84:87]
	v_mfma_f32_16x16x32_bf16 v[80:83], v[188:191], v[212:215], v[80:83]
	v_mfma_f32_16x16x32_bf16 v[68:71], v[180:183], v[220:223], v[68:71]
	v_mfma_f32_16x16x32_bf16 v[64:67], v[188:191], v[220:223], v[64:67]
	v_mfma_f32_16x16x32_bf16 v[116:119], v[184:187], v[200:203], v[116:119]
	v_mfma_f32_16x16x32_bf16 v[112:115], v[192:195], v[200:203], v[112:115]
	v_mfma_f32_16x16x32_bf16 v[100:103], v[184:187], v[208:211], v[100:103]
	v_mfma_f32_16x16x32_bf16 v[96:99], v[192:195], v[208:211], v[96:99]
	v_mfma_f32_16x16x32_bf16 v[84:87], v[184:187], v[216:219], v[84:87]
	v_mfma_f32_16x16x32_bf16 v[80:83], v[192:195], v[216:219], v[80:83]
	v_mfma_f32_16x16x32_bf16 v[68:71], v[184:187], v[224:227], v[68:71]
	v_mfma_f32_16x16x32_bf16 v[64:67], v[192:195], v[224:227], v[64:67]
	s_barrier
	s_add_i32 s36, s54, s40
	v_lshl_add_u64 v[148:149], v[148:149], 0, s[10:11]
	s_mov_b32 m0, s36
	ds_read_b128 v[196:199], v155 offset:49152
	ds_read_b128 v[200:203], v155 offset:50176
	ds_read_b128 v[204:207], v155 offset:51200
	ds_read_b128 v[208:211], v155 offset:52224
	ds_read_b128 v[212:215], v155 offset:53248
	ds_read_b128 v[216:219], v155 offset:54272
	ds_read_b128 v[220:223], v155 offset:55296
	ds_read_b128 v[224:227], v155 offset:56320
	global_load_lds_dwordx4 v[148:149], off
	s_add_i32 m0, s36, 0x2000
	s_add_u32 s34, s34, 0x40080
	v_lshl_add_u64 v[148:149], v[168:169], 0, s[10:11]
	s_addc_u32 s35, s35, 0
	s_add_i32 s36, s55, s40
	global_load_lds_dwordx4 v[148:149], off
	s_mov_b32 m0, s36
	v_lshl_add_u64 v[148:149], s[34:35], 0, v[142:143]
	global_load_lds_dwordx4 v[148:149], off
	s_add_i32 m0, s36, 0x2000
	v_lshl_add_u64 v[148:149], s[34:35], 0, v[146:147]
	global_load_lds_dwordx4 v[148:149], off
	s_mov_b32 m0, s44
	v_lshl_add_u64 v[148:149], v[228:229], 0, s[10:11]
	global_load_lds_dwordx4 v[148:149], off
	s_mov_b32 m0, s45
	v_lshl_add_u64 v[148:149], v[230:231], 0, s[10:11]
	global_load_lds_dwordx4 v[148:149], off
	s_waitcnt vmcnt(8) lgkmcnt(0)
	s_barrier
	v_mfma_f32_16x16x32_bf16 v[60:63], v[136:139], v[196:199], v[60:63]
	v_mfma_f32_16x16x32_bf16 v[56:59], v[160:163], v[196:199], v[56:59]
	v_mfma_f32_16x16x32_bf16 v[44:47], v[136:139], v[204:207], v[44:47]
	v_mfma_f32_16x16x32_bf16 v[40:43], v[160:163], v[204:207], v[40:43]
	v_mfma_f32_16x16x32_bf16 v[28:31], v[136:139], v[212:215], v[28:31]
	v_mfma_f32_16x16x32_bf16 v[24:27], v[160:163], v[212:215], v[24:27]
	v_mfma_f32_16x16x32_bf16 v[12:15], v[136:139], v[220:223], v[12:15]
	v_mfma_f32_16x16x32_bf16 v[8:11], v[160:163], v[220:223], v[8:11]
	v_mfma_f32_16x16x32_bf16 v[60:63], v[156:159], v[200:203], v[60:63]
	v_mfma_f32_16x16x32_bf16 v[56:59], v[164:167], v[200:203], v[56:59]
	v_mfma_f32_16x16x32_bf16 v[44:47], v[156:159], v[208:211], v[44:47]
	v_mfma_f32_16x16x32_bf16 v[40:43], v[164:167], v[208:211], v[40:43]
	v_mfma_f32_16x16x32_bf16 v[28:31], v[156:159], v[216:219], v[28:31]
	v_mfma_f32_16x16x32_bf16 v[24:27], v[164:167], v[216:219], v[24:27]
	v_mfma_f32_16x16x32_bf16 v[12:15], v[156:159], v[224:227], v[12:15]
	v_mfma_f32_16x16x32_bf16 v[8:11], v[164:167], v[224:227], v[8:11]
	v_mfma_f32_16x16x32_bf16 v[52:55], v[180:183], v[196:199], v[52:55]
	v_mfma_f32_16x16x32_bf16 v[48:51], v[188:191], v[196:199], v[48:51]
	v_mfma_f32_16x16x32_bf16 v[36:39], v[180:183], v[204:207], v[36:39]
	v_mfma_f32_16x16x32_bf16 v[32:35], v[188:191], v[204:207], v[32:35]
	v_mfma_f32_16x16x32_bf16 v[20:23], v[180:183], v[212:215], v[20:23]
	v_mfma_f32_16x16x32_bf16 v[16:19], v[188:191], v[212:215], v[16:19]
	v_mfma_f32_16x16x32_bf16 v[4:7], v[180:183], v[220:223], v[4:7]
	v_mfma_f32_16x16x32_bf16 v[0:3], v[188:191], v[220:223], v[0:3]
	v_mfma_f32_16x16x32_bf16 v[52:55], v[184:187], v[200:203], v[52:55]
	v_mfma_f32_16x16x32_bf16 v[48:51], v[192:195], v[200:203], v[48:51]
	v_mfma_f32_16x16x32_bf16 v[36:39], v[184:187], v[208:211], v[36:39]
	v_mfma_f32_16x16x32_bf16 v[32:35], v[192:195], v[208:211], v[32:35]
	v_mfma_f32_16x16x32_bf16 v[20:23], v[184:187], v[216:219], v[20:23]
	v_mfma_f32_16x16x32_bf16 v[16:19], v[192:195], v[216:219], v[16:19]
	v_mfma_f32_16x16x32_bf16 v[4:7], v[184:187], v[224:227], v[4:7]
	v_mfma_f32_16x16x32_bf16 v[0:3], v[192:195], v[224:227], v[0:3]
	s_barrier
	s_add_i32 s53, s53, 2
	s_add_u32 s30, s30, 0x100
	s_addc_u32 s31, s31, 0
	s_add_u32 s51, s51, 0x100
	s_addc_u32 s52, s52, 0
	s_cmp_gt_u32 s53, 13
	s_cbranch_scc0 .LBB0_686
	s_and_b64 vcc, exec, s[12:13]
	s_cbranch_vccz .LBB0_689
	s_barrier

.LBB0_758:
	ds_read_b128 v[140:143], v183
	ds_read_b128 v[144:147], v183 offset:1024
	ds_read_b128 v[148:151], v183 offset:2048
	ds_read_b128 v[152:155], v183 offset:3072
	ds_read_b128 v[156:159], v184
	ds_read_b128 v[160:163], v184 offset:1024
	ds_read_b128 v[164:167], v184 offset:2048
	ds_read_b128 v[186:189], v184 offset:3072
	s_add_u32 s36, s34, 0xfffc0080
	s_addc_u32 s37, s35, -1
	s_cmp_eq_u32 s60, 12
	s_cselect_b32 s39, s25, s37
	s_cselect_b32 s38, s54, s36
	s_cselect_b32 s37, s23, s57
	s_cselect_b32 s36, s55, s56
	v_lshl_add_u64 v[222:223], s[34:35], 0, v[132:133]
	s_add_i32 m0, s31, 0xc000
	ds_read_b128 v[190:193], v185
	ds_read_b128 v[194:197], v185 offset:1024
	ds_read_b128 v[198:201], v185 offset:2048
	ds_read_b128 v[202:205], v185 offset:3072
	ds_read_b128 v[206:209], v185 offset:4096
	ds_read_b128 v[210:213], v185 offset:5120
	ds_read_b128 v[214:217], v185 offset:6144
	ds_read_b128 v[218:221], v185 offset:7168
	global_load_lds_dwordx4 v[222:223], off
	s_add_i32 m0, s31, 0xe000
	v_lshl_add_u64 v[222:223], s[34:35], 0, v[134:135]
	global_load_lds_dwordx4 v[222:223], off
	s_waitcnt vmcnt(8) lgkmcnt(0)
	s_barrier
	v_mfma_f32_16x16x32_bf16 v[124:127], v[140:143], v[190:193], v[124:127]
	v_mfma_f32_16x16x32_bf16 v[120:123], v[148:151], v[190:193], v[120:123]
	v_mfma_f32_16x16x32_bf16 v[108:111], v[140:143], v[198:201], v[108:111]
	v_mfma_f32_16x16x32_bf16 v[104:107], v[148:151], v[198:201], v[104:107]
	v_mfma_f32_16x16x32_bf16 v[92:95], v[140:143], v[206:209], v[92:95]
	v_mfma_f32_16x16x32_bf16 v[88:91], v[148:151], v[206:209], v[88:91]
	v_mfma_f32_16x16x32_bf16 v[76:79], v[140:143], v[214:217], v[76:79]
	v_mfma_f32_16x16x32_bf16 v[72:75], v[148:151], v[214:217], v[72:75]
	v_mfma_f32_16x16x32_bf16 v[124:127], v[144:147], v[194:197], v[124:127]
	v_mfma_f32_16x16x32_bf16 v[120:123], v[152:155], v[194:197], v[120:123]
	v_mfma_f32_16x16x32_bf16 v[108:111], v[144:147], v[202:205], v[108:111]
	v_mfma_f32_16x16x32_bf16 v[104:107], v[152:155], v[202:205], v[104:107]
	v_mfma_f32_16x16x32_bf16 v[92:95], v[144:147], v[210:213], v[92:95]
	v_mfma_f32_16x16x32_bf16 v[88:91], v[152:155], v[210:213], v[88:91]
	v_mfma_f32_16x16x32_bf16 v[76:79], v[144:147], v[218:221], v[76:79]
	v_mfma_f32_16x16x32_bf16 v[72:75], v[152:155], v[218:221], v[72:75]
	v_mfma_f32_16x16x32_bf16 v[116:119], v[156:159], v[190:193], v[116:119]
	v_mfma_f32_16x16x32_bf16 v[112:115], v[164:167], v[190:193], v[112:115]
	v_mfma_f32_16x16x32_bf16 v[100:103], v[156:159], v[198:201], v[100:103]
	v_mfma_f32_16x16x32_bf16 v[96:99], v[164:167], v[198:201], v[96:99]
	v_mfma_f32_16x16x32_bf16 v[84:87], v[156:159], v[206:209], v[84:87]
	v_mfma_f32_16x16x32_bf16 v[80:83], v[164:167], v[206:209], v[80:83]
	v_mfma_f32_16x16x32_bf16 v[68:71], v[156:159], v[214:217], v[68:71]
	v_mfma_f32_16x16x32_bf16 v[64:67], v[164:167], v[214:217], v[64:67]
	v_mfma_f32_16x16x32_bf16 v[116:119], v[160:163], v[194:197], v[116:119]
	v_mfma_f32_16x16x32_bf16 v[112:115], v[186:189], v[194:197], v[112:115]
	v_mfma_f32_16x16x32_bf16 v[100:103], v[160:163], v[202:205], v[100:103]
	v_mfma_f32_16x16x32_bf16 v[96:99], v[186:189], v[202:205], v[96:99]
	v_mfma_f32_16x16x32_bf16 v[84:87], v[160:163], v[210:213], v[84:87]
	v_mfma_f32_16x16x32_bf16 v[80:83], v[186:189], v[210:213], v[80:83]
	v_mfma_f32_16x16x32_bf16 v[68:71], v[160:163], v[218:221], v[68:71]
	v_mfma_f32_16x16x32_bf16 v[64:67], v[186:189], v[218:221], v[64:67]
	s_barrier
	s_add_i32 s61, s51, s42
	v_lshl_add_u64 v[222:223], s[36:37], 0, v[128:129]
	s_mov_b32 m0, s61
	ds_read_b128 v[190:193], v185 offset:16384
	ds_read_b128 v[194:197], v185 offset:17408
	ds_read_b128 v[198:201], v185 offset:18432
	ds_read_b128 v[202:205], v185 offset:19456
	ds_read_b128 v[206:209], v185 offset:20480
	ds_read_b128 v[210:213], v185 offset:21504
	ds_read_b128 v[214:217], v185 offset:22528
	ds_read_b128 v[218:221], v185 offset:23552
	global_load_lds_dwordx4 v[222:223], off
	s_add_i32 m0, s61, 0x2000
	s_add_u32 s62, s36, 0x40000
	v_lshl_add_u64 v[224:225], s[36:37], 0, v[130:131]
	s_addc_u32 s63, s37, 0
	s_add_i32 s61, s52, s42
	global_load_lds_dwordx4 v[224:225], off
	v_lshl_add_u64 v[226:227], s[62:63], 0, v[128:129]
	s_mov_b32 m0, s61
	v_lshl_add_u64 v[228:229], s[38:39], 0, v[130:131]
	global_load_lds_dwordx4 v[226:227], off
	s_add_i32 m0, s61, 0x2000
	v_lshl_add_u64 v[226:227], s[62:63], 0, v[130:131]
	global_load_lds_dwordx4 v[226:227], off
	s_mov_b32 m0, s31
	v_lshl_add_u64 v[226:227], s[38:39], 0, v[128:129]
	global_load_lds_dwordx4 v[226:227], off
	s_mov_b32 m0, s43
	s_nop 0
	global_load_lds_dwordx4 v[228:229], off
	s_waitcnt vmcnt(8) lgkmcnt(0)
	s_barrier
	v_mfma_f32_16x16x32_bf16 v[60:63], v[140:143], v[190:193], v[60:63]
	v_mfma_f32_16x16x32_bf16 v[56:59], v[148:151], v[190:193], v[56:59]
	v_mfma_f32_16x16x32_bf16 v[44:47], v[140:143], v[198:201], v[44:47]
	v_mfma_f32_16x16x32_bf16 v[40:43], v[148:151], v[198:201], v[40:43]
	v_mfma_f32_16x16x32_bf16 v[28:31], v[140:143], v[206:209], v[28:31]
	v_mfma_f32_16x16x32_bf16 v[24:27], v[148:151], v[206:209], v[24:27]
	v_mfma_f32_16x16x32_bf16 v[12:15], v[140:143], v[214:217], v[12:15]
	v_mfma_f32_16x16x32_bf16 v[8:11], v[148:151], v[214:217], v[8:11]
	v_mfma_f32_16x16x32_bf16 v[60:63], v[144:147], v[194:197], v[60:63]
	v_mfma_f32_16x16x32_bf16 v[56:59], v[152:155], v[194:197], v[56:59]
	v_mfma_f32_16x16x32_bf16 v[44:47], v[144:147], v[202:205], v[44:47]
	v_mfma_f32_16x16x32_bf16 v[40:43], v[152:155], v[202:205], v[40:43]
	v_mfma_f32_16x16x32_bf16 v[28:31], v[144:147], v[210:213], v[28:31]
	v_mfma_f32_16x16x32_bf16 v[24:27], v[152:155], v[210:213], v[24:27]
	v_mfma_f32_16x16x32_bf16 v[12:15], v[144:147], v[218:221], v[12:15]
	v_mfma_f32_16x16x32_bf16 v[8:11], v[152:155], v[218:221], v[8:11]
	v_mfma_f32_16x16x32_bf16 v[52:55], v[156:159], v[190:193], v[52:55]
	v_mfma_f32_16x16x32_bf16 v[48:51], v[164:167], v[190:193], v[48:51]
	v_mfma_f32_16x16x32_bf16 v[36:39], v[156:159], v[198:201], v[36:39]
	v_mfma_f32_16x16x32_bf16 v[32:35], v[164:167], v[198:201], v[32:35]
	v_mfma_f32_16x16x32_bf16 v[20:23], v[156:159], v[206:209], v[20:23]
	v_mfma_f32_16x16x32_bf16 v[16:19], v[164:167], v[206:209], v[16:19]
	v_mfma_f32_16x16x32_bf16 v[4:7], v[156:159], v[214:217], v[4:7]
	v_mfma_f32_16x16x32_bf16 v[0:3], v[164:167], v[214:217], v[0:3]
	v_mfma_f32_16x16x32_bf16 v[52:55], v[160:163], v[194:197], v[52:55]
	v_mfma_f32_16x16x32_bf16 v[48:51], v[186:189], v[194:197], v[48:51]
	v_mfma_f32_16x16x32_bf16 v[36:39], v[160:163], v[202:205], v[36:39]
	v_mfma_f32_16x16x32_bf16 v[32:35], v[186:189], v[202:205], v[32:35]
	v_mfma_f32_16x16x32_bf16 v[20:23], v[160:163], v[210:213], v[20:23]
	v_mfma_f32_16x16x32_bf16 v[16:19], v[186:189], v[210:213], v[16:19]
	v_mfma_f32_16x16x32_bf16 v[4:7], v[160:163], v[218:221], v[4:7]
	v_mfma_f32_16x16x32_bf16 v[0:3], v[186:189], v[218:221], v[0:3]
	s_barrier
	s_add_i32 s61, 0, 0x18000
	s_add_i32 s62, 0, 0x1c000
	v_add_u32_e32 v152, s61, v181
	v_add_u32_e32 v186, s62, v181
	ds_read_b128 v[140:143], v152
	ds_read_b128 v[144:147], v152 offset:1024
	ds_read_b128 v[148:151], v152 offset:2048
	ds_read_b128 v[152:155], v152 offset:3072
	ds_read_b128 v[156:159], v186
	ds_read_b128 v[160:163], v186 offset:1024
	ds_read_b128 v[164:167], v186 offset:2048
	ds_read_b128 v[186:189], v186 offset:3072
	s_add_u32 s38, s38, 0x40000
	s_addc_u32 s39, s39, 0
	s_mov_b32 m0, s44
	v_lshl_add_u64 v[230:231], s[38:39], 0, v[128:129]
	ds_read_b128 v[190:193], v185 offset:32768
	ds_read_b128 v[194:197], v185 offset:33792
	ds_read_b128 v[198:201], v185 offset:34816
	ds_read_b128 v[202:205], v185 offset:35840
	ds_read_b128 v[206:209], v185 offset:36864
	ds_read_b128 v[210:213], v185 offset:37888
	ds_read_b128 v[214:217], v185 offset:38912
	ds_read_b128 v[218:221], v185 offset:39936
	global_load_lds_dwordx4 v[230:231], off
	s_mov_b32 m0, s45
	v_lshl_add_u64 v[230:231], s[38:39], 0, v[130:131]
	global_load_lds_dwordx4 v[230:231], off
	s_waitcnt vmcnt(8) lgkmcnt(0)
	s_barrier
	v_mfma_f32_16x16x32_bf16 v[124:127], v[140:143], v[190:193], v[124:127]
	v_mfma_f32_16x16x32_bf16 v[120:123], v[148:151], v[190:193], v[120:123]
	v_mfma_f32_16x16x32_bf16 v[108:111], v[140:143], v[198:201], v[108:111]
	v_mfma_f32_16x16x32_bf16 v[104:107], v[148:151], v[198:201], v[104:107]
	v_mfma_f32_16x16x32_bf16 v[92:95], v[140:143], v[206:209], v[92:95]
	v_mfma_f32_16x16x32_bf16 v[88:91], v[148:151], v[206:209], v[88:91]
	v_mfma_f32_16x16x32_bf16 v[76:79], v[140:143], v[214:217], v[76:79]
	v_mfma_f32_16x16x32_bf16 v[72:75], v[148:151], v[214:217], v[72:75]
	v_mfma_f32_16x16x32_bf16 v[124:127], v[144:147], v[194:197], v[124:127]
	v_mfma_f32_16x16x32_bf16 v[120:123], v[152:155], v[194:197], v[120:123]
	v_mfma_f32_16x16x32_bf16 v[108:111], v[144:147], v[202:205], v[108:111]
	v_mfma_f32_16x16x32_bf16 v[104:107], v[152:155], v[202:205], v[104:107]
	v_mfma_f32_16x16x32_bf16 v[92:95], v[144:147], v[210:213], v[92:95]
	v_mfma_f32_16x16x32_bf16 v[88:91], v[152:155], v[210:213], v[88:91]
	v_mfma_f32_16x16x32_bf16 v[76:79], v[144:147], v[218:221], v[76:79]
	v_mfma_f32_16x16x32_bf16 v[72:75], v[152:155], v[218:221], v[72:75]
	v_mfma_f32_16x16x32_bf16 v[116:119], v[156:159], v[190:193], v[116:119]
	v_mfma_f32_16x16x32_bf16 v[112:115], v[164:167], v[190:193], v[112:115]
	v_mfma_f32_16x16x32_bf16 v[100:103], v[156:159], v[198:201], v[100:103]
	v_mfma_f32_16x16x32_bf16 v[96:99], v[164:167], v[198:201], v[96:99]
	v_mfma_f32_16x16x32_bf16 v[84:87], v[156:159], v[206:209], v[84:87]
	v_mfma_f32_16x16x32_bf16 v[80:83], v[164:167], v[206:209], v[80:83]
	v_mfma_f32_16x16x32_bf16 v[68:71], v[156:159], v[214:217], v[68:71]
	v_mfma_f32_16x16x32_bf16 v[64:67], v[164:167], v[214:217], v[64:67]
	v_mfma_f32_16x16x32_bf16 v[116:119], v[160:163], v[194:197], v[116:119]
	v_mfma_f32_16x16x32_bf16 v[112:115], v[186:189], v[194:197], v[112:115]
	v_mfma_f32_16x16x32_bf16 v[100:103], v[160:163], v[202:205], v[100:103]
	v_mfma_f32_16x16x32_bf16 v[96:99], v[186:189], v[202:205], v[96:99]
	v_mfma_f32_16x16x32_bf16 v[84:87], v[160:163], v[210:213], v[84:87]
	v_mfma_f32_16x16x32_bf16 v[80:83], v[186:189], v[210:213], v[80:83]
	v_mfma_f32_16x16x32_bf16 v[68:71], v[160:163], v[218:221], v[68:71]
	v_mfma_f32_16x16x32_bf16 v[64:67], v[186:189], v[218:221], v[64:67]
	s_barrier
	s_add_i32 s38, s61, s42
	v_lshl_add_u64 v[222:223], v[222:223], 0, s[12:13]
	s_mov_b32 m0, s38
	ds_read_b128 v[190:193], v185 offset:49152
	ds_read_b128 v[194:197], v185 offset:50176
	ds_read_b128 v[198:201], v185 offset:51200
	ds_read_b128 v[202:205], v185 offset:52224
	ds_read_b128 v[206:209], v185 offset:53248
	ds_read_b128 v[210:213], v185 offset:54272
	ds_read_b128 v[214:217], v185 offset:55296
	ds_read_b128 v[218:221], v185 offset:56320
	global_load_lds_dwordx4 v[222:223], off
	s_add_i32 m0, s38, 0x2000
	s_add_u32 s36, s36, 0x40080
	v_lshl_add_u64 v[222:223], v[224:225], 0, s[12:13]
	s_addc_u32 s37, s37, 0
	s_add_i32 s38, s62, s42
	global_load_lds_dwordx4 v[222:223], off
	s_mov_b32 m0, s38
	v_lshl_add_u64 v[222:223], s[36:37], 0, v[128:129]
	global_load_lds_dwordx4 v[222:223], off
	s_add_i32 m0, s38, 0x2000
	v_lshl_add_u64 v[222:223], s[36:37], 0, v[130:131]
	global_load_lds_dwordx4 v[222:223], off
	s_mov_b32 m0, s48
	v_lshl_add_u64 v[222:223], v[226:227], 0, s[12:13]
	global_load_lds_dwordx4 v[222:223], off
	s_mov_b32 m0, s49
	v_lshl_add_u64 v[222:223], v[228:229], 0, s[12:13]
	global_load_lds_dwordx4 v[222:223], off
	s_waitcnt vmcnt(8) lgkmcnt(0)
	s_barrier
	v_mfma_f32_16x16x32_bf16 v[60:63], v[140:143], v[190:193], v[60:63]
	v_mfma_f32_16x16x32_bf16 v[56:59], v[148:151], v[190:193], v[56:59]
	v_mfma_f32_16x16x32_bf16 v[44:47], v[140:143], v[198:201], v[44:47]
	v_mfma_f32_16x16x32_bf16 v[40:43], v[148:151], v[198:201], v[40:43]
	v_mfma_f32_16x16x32_bf16 v[28:31], v[140:143], v[206:209], v[28:31]
	v_mfma_f32_16x16x32_bf16 v[24:27], v[148:151], v[206:209], v[24:27]
	v_mfma_f32_16x16x32_bf16 v[12:15], v[140:143], v[214:217], v[12:15]
	v_mfma_f32_16x16x32_bf16 v[8:11], v[148:151], v[214:217], v[8:11]
	v_mfma_f32_16x16x32_bf16 v[60:63], v[144:147], v[194:197], v[60:63]
	v_mfma_f32_16x16x32_bf16 v[56:59], v[152:155], v[194:197], v[56:59]
	v_mfma_f32_16x16x32_bf16 v[44:47], v[144:147], v[202:205], v[44:47]
	v_mfma_f32_16x16x32_bf16 v[40:43], v[152:155], v[202:205], v[40:43]
	v_mfma_f32_16x16x32_bf16 v[28:31], v[144:147], v[210:213], v[28:31]
	v_mfma_f32_16x16x32_bf16 v[24:27], v[152:155], v[210:213], v[24:27]
	v_mfma_f32_16x16x32_bf16 v[12:15], v[144:147], v[218:221], v[12:15]
	v_mfma_f32_16x16x32_bf16 v[8:11], v[152:155], v[218:221], v[8:11]
	v_mfma_f32_16x16x32_bf16 v[52:55], v[156:159], v[190:193], v[52:55]
	v_mfma_f32_16x16x32_bf16 v[48:51], v[164:167], v[190:193], v[48:51]
	v_mfma_f32_16x16x32_bf16 v[36:39], v[156:159], v[198:201], v[36:39]
	v_mfma_f32_16x16x32_bf16 v[32:35], v[164:167], v[198:201], v[32:35]
	v_mfma_f32_16x16x32_bf16 v[20:23], v[156:159], v[206:209], v[20:23]
	v_mfma_f32_16x16x32_bf16 v[16:19], v[164:167], v[206:209], v[16:19]
	v_mfma_f32_16x16x32_bf16 v[4:7], v[156:159], v[214:217], v[4:7]
	v_mfma_f32_16x16x32_bf16 v[0:3], v[164:167], v[214:217], v[0:3]
	v_mfma_f32_16x16x32_bf16 v[52:55], v[160:163], v[194:197], v[52:55]
	v_mfma_f32_16x16x32_bf16 v[48:51], v[186:189], v[194:197], v[48:51]
	v_mfma_f32_16x16x32_bf16 v[36:39], v[160:163], v[202:205], v[36:39]
	v_mfma_f32_16x16x32_bf16 v[32:35], v[186:189], v[202:205], v[32:35]
	v_mfma_f32_16x16x32_bf16 v[20:23], v[160:163], v[210:213], v[20:23]
	v_mfma_f32_16x16x32_bf16 v[16:19], v[186:189], v[210:213], v[16:19]
	v_mfma_f32_16x16x32_bf16 v[4:7], v[160:163], v[218:221], v[4:7]
	v_mfma_f32_16x16x32_bf16 v[0:3], v[186:189], v[218:221], v[0:3]
	s_barrier
	s_add_i32 s60, s60, 2
	s_add_u32 s34, s34, 0x100
	s_addc_u32 s35, s35, 0
	s_add_u32 s56, s56, 0x100
	s_addc_u32 s57, s57, 0
	s_cmp_gt_u32 s60, 13
	s_cbranch_scc0 .LBB0_758
	s_and_b64 vcc, exec, s[14:15]
	s_cbranch_vccz .LBB0_761
	s_barrier

.LBB0_778:
	v_add_u32_e32 v147, s43, v145
	ds_read_b128 v[148:151], v147
	ds_read_b128 v[152:155], v147 offset:1024
	ds_read_b128 v[156:159], v147 offset:2048
	ds_read_b128 v[160:163], v147 offset:3072
	v_add_u32_e32 v147, s44, v145
	s_add_u32 s26, s12, s24
	ds_read_b128 v[164:167], v147
	ds_read_b128 v[180:183], v147 offset:1024
	ds_read_b128 v[184:187], v147 offset:2048
	ds_read_b128 v[188:191], v147 offset:3072
	s_addc_u32 s27, s13, s25
	s_add_u32 s26, s26, 0x100
	s_addc_u32 s27, s27, 0
	s_add_u32 s51, s46, s24
	s_addc_u32 s52, s47, s25
	s_cmpk_eq_i32 s24, 0x700
	s_cselect_b32 s29, s19, s27
	s_cselect_b32 s28, s48, s26
	s_cselect_b32 s27, s17, s52
	s_cselect_b32 s26, s49, s51
	v_lshl_add_u64 v[168:169], v[140:141], 0, s[24:25]
	s_add_i32 m0, s11, 0xc000
	ds_read_b128 v[192:195], v146
	ds_read_b128 v[196:199], v146 offset:1024
	ds_read_b128 v[200:203], v146 offset:2048
	ds_read_b128 v[204:207], v146 offset:3072
	ds_read_b128 v[208:211], v146 offset:4096
	ds_read_b128 v[212:215], v146 offset:5120
	ds_read_b128 v[216:219], v146 offset:6144
	ds_read_b128 v[220:223], v146 offset:7168
	global_load_lds_dwordx4 v[168:169], off
	s_add_i32 m0, s11, 0xe000
	v_lshl_add_u64 v[168:169], v[142:143], 0, s[24:25]
	global_load_lds_dwordx4 v[168:169], off
	s_waitcnt vmcnt(8) lgkmcnt(0)
	s_barrier
	v_mfma_f32_16x16x32_bf16 v[100:103], v[148:151], v[192:195], v[100:103]
	v_mfma_f32_16x16x32_bf16 v[96:99], v[156:159], v[192:195], v[96:99]
	v_mfma_f32_16x16x32_bf16 v[108:111], v[148:151], v[200:203], v[108:111]
	v_mfma_f32_16x16x32_bf16 v[84:87], v[156:159], v[200:203], v[84:87]
	v_mfma_f32_16x16x32_bf16 v[116:119], v[148:151], v[208:211], v[116:119]
	v_mfma_f32_16x16x32_bf16 v[112:115], v[156:159], v[208:211], v[112:115]
	v_mfma_f32_16x16x32_bf16 v[124:127], v[148:151], v[216:219], v[124:127]
	v_mfma_f32_16x16x32_bf16 v[120:123], v[156:159], v[216:219], v[120:123]
	v_mfma_f32_16x16x32_bf16 v[100:103], v[152:155], v[196:199], v[100:103]
	v_mfma_f32_16x16x32_bf16 v[96:99], v[160:163], v[196:199], v[96:99]
	v_mfma_f32_16x16x32_bf16 v[108:111], v[152:155], v[204:207], v[108:111]
	v_mfma_f32_16x16x32_bf16 v[84:87], v[160:163], v[204:207], v[84:87]
	v_mfma_f32_16x16x32_bf16 v[116:119], v[152:155], v[212:215], v[116:119]
	v_mfma_f32_16x16x32_bf16 v[112:115], v[160:163], v[212:215], v[112:115]
	v_mfma_f32_16x16x32_bf16 v[124:127], v[152:155], v[220:223], v[124:127]
	v_mfma_f32_16x16x32_bf16 v[120:123], v[160:163], v[220:223], v[120:123]
	v_mfma_f32_16x16x32_bf16 v[76:79], v[164:167], v[192:195], v[76:79]
	v_mfma_f32_16x16x32_bf16 v[68:71], v[184:187], v[192:195], v[68:71]
	v_mfma_f32_16x16x32_bf16 v[72:75], v[164:167], v[200:203], v[72:75]
	v_mfma_f32_16x16x32_bf16 v[64:67], v[184:187], v[200:203], v[64:67]
	v_mfma_f32_16x16x32_bf16 v[88:91], v[164:167], v[208:211], v[88:91]
	v_mfma_f32_16x16x32_bf16 v[80:83], v[184:187], v[208:211], v[80:83]
	v_mfma_f32_16x16x32_bf16 v[104:107], v[164:167], v[216:219], v[104:107]
	v_mfma_f32_16x16x32_bf16 v[92:95], v[184:187], v[216:219], v[92:95]
	v_mfma_f32_16x16x32_bf16 v[76:79], v[180:183], v[196:199], v[76:79]
	v_mfma_f32_16x16x32_bf16 v[68:71], v[188:191], v[196:199], v[68:71]
	v_mfma_f32_16x16x32_bf16 v[72:75], v[180:183], v[204:207], v[72:75]
	v_mfma_f32_16x16x32_bf16 v[64:67], v[188:191], v[204:207], v[64:67]
	v_mfma_f32_16x16x32_bf16 v[88:91], v[180:183], v[212:215], v[88:91]
	v_mfma_f32_16x16x32_bf16 v[80:83], v[188:191], v[212:215], v[80:83]
	v_mfma_f32_16x16x32_bf16 v[104:107], v[180:183], v[220:223], v[104:107]
	v_mfma_f32_16x16x32_bf16 v[92:95], v[188:191], v[220:223], v[92:95]
	s_barrier
	s_add_i32 s51, s43, s35
	v_lshl_add_u64 v[168:169], s[26:27], 0, v[128:129]
	s_mov_b32 m0, s51
	ds_read_b128 v[192:195], v146 offset:16384
	ds_read_b128 v[196:199], v146 offset:17408
	ds_read_b128 v[200:203], v146 offset:18432
	ds_read_b128 v[204:207], v146 offset:19456
	ds_read_b128 v[208:211], v146 offset:20480
	ds_read_b128 v[212:215], v146 offset:21504
	ds_read_b128 v[216:219], v146 offset:22528
	ds_read_b128 v[220:223], v146 offset:23552
	global_load_lds_dwordx4 v[168:169], off
	s_add_i32 m0, s51, 0x2000
	s_add_u32 s52, s26, 0x40000
	v_lshl_add_u64 v[224:225], s[26:27], 0, v[130:131]
	s_addc_u32 s53, s27, 0
	s_add_i32 s51, s44, s35
	global_load_lds_dwordx4 v[224:225], off
	v_lshl_add_u64 v[226:227], s[52:53], 0, v[128:129]
	s_mov_b32 m0, s51
	v_lshl_add_u64 v[228:229], s[28:29], 0, v[130:131]
	global_load_lds_dwordx4 v[226:227], off
	s_add_i32 m0, s51, 0x2000
	v_lshl_add_u64 v[226:227], s[52:53], 0, v[130:131]
	global_load_lds_dwordx4 v[226:227], off
	s_mov_b32 m0, s11
	v_lshl_add_u64 v[226:227], s[28:29], 0, v[128:129]
	global_load_lds_dwordx4 v[226:227], off
	s_mov_b32 m0, s36
	s_nop 0
	global_load_lds_dwordx4 v[228:229], off
	s_waitcnt vmcnt(8) lgkmcnt(0)
	s_barrier
	v_mfma_f32_16x16x32_bf16 v[60:63], v[148:151], v[192:195], v[60:63]
	v_mfma_f32_16x16x32_bf16 v[56:59], v[156:159], v[192:195], v[56:59]
	v_mfma_f32_16x16x32_bf16 v[44:47], v[148:151], v[200:203], v[44:47]
	v_mfma_f32_16x16x32_bf16 v[40:43], v[156:159], v[200:203], v[40:43]
	v_mfma_f32_16x16x32_bf16 v[28:31], v[148:151], v[208:211], v[28:31]
	v_mfma_f32_16x16x32_bf16 v[24:27], v[156:159], v[208:211], v[24:27]
	v_mfma_f32_16x16x32_bf16 v[12:15], v[148:151], v[216:219], v[12:15]
	v_mfma_f32_16x16x32_bf16 v[8:11], v[156:159], v[216:219], v[8:11]
	v_mfma_f32_16x16x32_bf16 v[60:63], v[152:155], v[196:199], v[60:63]
	v_mfma_f32_16x16x32_bf16 v[56:59], v[160:163], v[196:199], v[56:59]
	v_mfma_f32_16x16x32_bf16 v[44:47], v[152:155], v[204:207], v[44:47]
	v_mfma_f32_16x16x32_bf16 v[40:43], v[160:163], v[204:207], v[40:43]
	v_mfma_f32_16x16x32_bf16 v[28:31], v[152:155], v[212:215], v[28:31]
	v_mfma_f32_16x16x32_bf16 v[24:27], v[160:163], v[212:215], v[24:27]
	v_mfma_f32_16x16x32_bf16 v[12:15], v[152:155], v[220:223], v[12:15]
	v_mfma_f32_16x16x32_bf16 v[8:11], v[160:163], v[220:223], v[8:11]
	v_mfma_f32_16x16x32_bf16 v[52:55], v[164:167], v[192:195], v[52:55]
	v_mfma_f32_16x16x32_bf16 v[48:51], v[184:187], v[192:195], v[48:51]
	v_mfma_f32_16x16x32_bf16 v[36:39], v[164:167], v[200:203], v[36:39]
	v_mfma_f32_16x16x32_bf16 v[32:35], v[184:187], v[200:203], v[32:35]
	v_mfma_f32_16x16x32_bf16 v[20:23], v[164:167], v[208:211], v[20:23]
	v_mfma_f32_16x16x32_bf16 v[16:19], v[184:187], v[208:211], v[16:19]
	v_mfma_f32_16x16x32_bf16 v[4:7], v[164:167], v[216:219], v[4:7]
	v_mfma_f32_16x16x32_bf16 v[0:3], v[184:187], v[216:219], v[0:3]
	v_mfma_f32_16x16x32_bf16 v[52:55], v[180:183], v[196:199], v[52:55]
	v_mfma_f32_16x16x32_bf16 v[48:51], v[188:191], v[196:199], v[48:51]
	v_mfma_f32_16x16x32_bf16 v[36:39], v[180:183], v[204:207], v[36:39]
	v_mfma_f32_16x16x32_bf16 v[32:35], v[188:191], v[204:207], v[32:35]
	v_mfma_f32_16x16x32_bf16 v[20:23], v[180:183], v[212:215], v[20:23]
	v_mfma_f32_16x16x32_bf16 v[16:19], v[188:191], v[212:215], v[16:19]
	v_mfma_f32_16x16x32_bf16 v[4:7], v[180:183], v[220:223], v[4:7]
	v_mfma_f32_16x16x32_bf16 v[0:3], v[188:191], v[220:223], v[0:3]
	s_barrier
	s_add_i32 s51, 0, 0x18000
	v_add_u32_e32 v147, s51, v145
	s_add_i32 s52, 0, 0x1c000
	ds_read_b128 v[148:151], v147
	ds_read_b128 v[152:155], v147 offset:1024
	ds_read_b128 v[156:159], v147 offset:2048
	ds_read_b128 v[160:163], v147 offset:3072
	v_add_u32_e32 v147, s52, v145
	ds_read_b128 v[164:167], v147
	ds_read_b128 v[180:183], v147 offset:1024
	ds_read_b128 v[184:187], v147 offset:2048
	ds_read_b128 v[188:191], v147 offset:3072
	s_add_u32 s28, s28, 0x40000
	s_addc_u32 s29, s29, 0
	s_mov_b32 m0, s37
	v_lshl_add_u64 v[230:231], s[28:29], 0, v[128:129]
	ds_read_b128 v[192:195], v146 offset:32768
	ds_read_b128 v[196:199], v146 offset:33792
	ds_read_b128 v[200:203], v146 offset:34816
	ds_read_b128 v[204:207], v146 offset:35840
	ds_read_b128 v[208:211], v146 offset:36864
	ds_read_b128 v[212:215], v146 offset:37888
	ds_read_b128 v[216:219], v146 offset:38912
	ds_read_b128 v[220:223], v146 offset:39936
	global_load_lds_dwordx4 v[230:231], off
	s_mov_b32 m0, s38
	v_lshl_add_u64 v[230:231], s[28:29], 0, v[130:131]
	global_load_lds_dwordx4 v[230:231], off
	s_waitcnt vmcnt(8) lgkmcnt(0)
	s_barrier
	v_mfma_f32_16x16x32_bf16 v[100:103], v[148:151], v[192:195], v[100:103]
	v_mfma_f32_16x16x32_bf16 v[96:99], v[156:159], v[192:195], v[96:99]
	v_mfma_f32_16x16x32_bf16 v[108:111], v[148:151], v[200:203], v[108:111]
	v_mfma_f32_16x16x32_bf16 v[84:87], v[156:159], v[200:203], v[84:87]
	v_mfma_f32_16x16x32_bf16 v[116:119], v[148:151], v[208:211], v[116:119]
	v_mfma_f32_16x16x32_bf16 v[112:115], v[156:159], v[208:211], v[112:115]
	v_mfma_f32_16x16x32_bf16 v[124:127], v[148:151], v[216:219], v[124:127]
	v_mfma_f32_16x16x32_bf16 v[120:123], v[156:159], v[216:219], v[120:123]
	v_mfma_f32_16x16x32_bf16 v[100:103], v[152:155], v[196:199], v[100:103]
	v_mfma_f32_16x16x32_bf16 v[96:99], v[160:163], v[196:199], v[96:99]
	v_mfma_f32_16x16x32_bf16 v[108:111], v[152:155], v[204:207], v[108:111]
	v_mfma_f32_16x16x32_bf16 v[84:87], v[160:163], v[204:207], v[84:87]
	v_mfma_f32_16x16x32_bf16 v[116:119], v[152:155], v[212:215], v[116:119]
	v_mfma_f32_16x16x32_bf16 v[112:115], v[160:163], v[212:215], v[112:115]
	v_mfma_f32_16x16x32_bf16 v[124:127], v[152:155], v[220:223], v[124:127]
	v_mfma_f32_16x16x32_bf16 v[120:123], v[160:163], v[220:223], v[120:123]
	v_mfma_f32_16x16x32_bf16 v[76:79], v[164:167], v[192:195], v[76:79]
	v_mfma_f32_16x16x32_bf16 v[68:71], v[184:187], v[192:195], v[68:71]
	v_mfma_f32_16x16x32_bf16 v[72:75], v[164:167], v[200:203], v[72:75]
	v_mfma_f32_16x16x32_bf16 v[64:67], v[184:187], v[200:203], v[64:67]
	v_mfma_f32_16x16x32_bf16 v[88:91], v[164:167], v[208:211], v[88:91]
	v_mfma_f32_16x16x32_bf16 v[80:83], v[184:187], v[208:211], v[80:83]
	v_mfma_f32_16x16x32_bf16 v[104:107], v[164:167], v[216:219], v[104:107]
	v_mfma_f32_16x16x32_bf16 v[92:95], v[184:187], v[216:219], v[92:95]
	v_mfma_f32_16x16x32_bf16 v[76:79], v[180:183], v[196:199], v[76:79]
	v_mfma_f32_16x16x32_bf16 v[68:71], v[188:191], v[196:199], v[68:71]
	v_mfma_f32_16x16x32_bf16 v[72:75], v[180:183], v[204:207], v[72:75]
	v_mfma_f32_16x16x32_bf16 v[64:67], v[188:191], v[204:207], v[64:67]
	v_mfma_f32_16x16x32_bf16 v[88:91], v[180:183], v[212:215], v[88:91]
	v_mfma_f32_16x16x32_bf16 v[80:83], v[188:191], v[212:215], v[80:83]
	v_mfma_f32_16x16x32_bf16 v[104:107], v[180:183], v[220:223], v[104:107]
	v_mfma_f32_16x16x32_bf16 v[92:95], v[188:191], v[220:223], v[92:95]
	s_barrier
	s_add_i32 s28, s51, s35
	v_lshl_add_u64 v[168:169], v[168:169], 0, s[14:15]
	s_mov_b32 m0, s28
	ds_read_b128 v[192:195], v146 offset:49152
	ds_read_b128 v[196:199], v146 offset:50176
	ds_read_b128 v[200:203], v146 offset:51200
	ds_read_b128 v[204:207], v146 offset:52224
	ds_read_b128 v[208:211], v146 offset:53248
	ds_read_b128 v[212:215], v146 offset:54272
	ds_read_b128 v[216:219], v146 offset:55296
	ds_read_b128 v[220:223], v146 offset:56320
	global_load_lds_dwordx4 v[168:169], off
	s_add_i32 m0, s28, 0x2000
	s_add_u32 s26, s26, 0x40080
	v_lshl_add_u64 v[168:169], v[224:225], 0, s[14:15]
	s_addc_u32 s27, s27, 0
	s_add_i32 s28, s52, s35
	global_load_lds_dwordx4 v[168:169], off
	s_mov_b32 m0, s28
	v_lshl_add_u64 v[168:169], s[26:27], 0, v[128:129]
	global_load_lds_dwordx4 v[168:169], off
	s_add_i32 m0, s28, 0x2000
	v_lshl_add_u64 v[168:169], s[26:27], 0, v[130:131]
	global_load_lds_dwordx4 v[168:169], off
	s_mov_b32 m0, s41
	v_lshl_add_u64 v[168:169], v[226:227], 0, s[14:15]
	global_load_lds_dwordx4 v[168:169], off
	s_mov_b32 m0, s42
	v_lshl_add_u64 v[168:169], v[228:229], 0, s[14:15]
	global_load_lds_dwordx4 v[168:169], off
	s_waitcnt vmcnt(8) lgkmcnt(0)
	s_barrier
	v_mfma_f32_16x16x32_bf16 v[60:63], v[148:151], v[192:195], v[60:63]
	v_mfma_f32_16x16x32_bf16 v[56:59], v[156:159], v[192:195], v[56:59]
	v_mfma_f32_16x16x32_bf16 v[44:47], v[148:151], v[200:203], v[44:47]
	v_mfma_f32_16x16x32_bf16 v[40:43], v[156:159], v[200:203], v[40:43]
	v_mfma_f32_16x16x32_bf16 v[28:31], v[148:151], v[208:211], v[28:31]
	v_mfma_f32_16x16x32_bf16 v[24:27], v[156:159], v[208:211], v[24:27]
	v_mfma_f32_16x16x32_bf16 v[12:15], v[148:151], v[216:219], v[12:15]
	v_mfma_f32_16x16x32_bf16 v[8:11], v[156:159], v[216:219], v[8:11]
	v_mfma_f32_16x16x32_bf16 v[60:63], v[152:155], v[196:199], v[60:63]
	v_mfma_f32_16x16x32_bf16 v[56:59], v[160:163], v[196:199], v[56:59]
	v_mfma_f32_16x16x32_bf16 v[44:47], v[152:155], v[204:207], v[44:47]
	v_mfma_f32_16x16x32_bf16 v[40:43], v[160:163], v[204:207], v[40:43]
	v_mfma_f32_16x16x32_bf16 v[28:31], v[152:155], v[212:215], v[28:31]
	v_mfma_f32_16x16x32_bf16 v[24:27], v[160:163], v[212:215], v[24:27]
	v_mfma_f32_16x16x32_bf16 v[12:15], v[152:155], v[220:223], v[12:15]
	v_mfma_f32_16x16x32_bf16 v[8:11], v[160:163], v[220:223], v[8:11]
	v_mfma_f32_16x16x32_bf16 v[52:55], v[164:167], v[192:195], v[52:55]
	v_mfma_f32_16x16x32_bf16 v[48:51], v[184:187], v[192:195], v[48:51]
	v_mfma_f32_16x16x32_bf16 v[36:39], v[164:167], v[200:203], v[36:39]
	v_mfma_f32_16x16x32_bf16 v[32:35], v[184:187], v[200:203], v[32:35]
	v_mfma_f32_16x16x32_bf16 v[20:23], v[164:167], v[208:211], v[20:23]
	v_mfma_f32_16x16x32_bf16 v[16:19], v[184:187], v[208:211], v[16:19]
	v_mfma_f32_16x16x32_bf16 v[4:7], v[164:167], v[216:219], v[4:7]
	v_mfma_f32_16x16x32_bf16 v[0:3], v[184:187], v[216:219], v[0:3]
	v_mfma_f32_16x16x32_bf16 v[52:55], v[180:183], v[196:199], v[52:55]
	v_mfma_f32_16x16x32_bf16 v[48:51], v[188:191], v[196:199], v[48:51]
	v_mfma_f32_16x16x32_bf16 v[36:39], v[180:183], v[204:207], v[36:39]
	v_mfma_f32_16x16x32_bf16 v[32:35], v[188:191], v[204:207], v[32:35]
	v_mfma_f32_16x16x32_bf16 v[20:23], v[180:183], v[212:215], v[20:23]
	v_mfma_f32_16x16x32_bf16 v[16:19], v[188:191], v[212:215], v[16:19]
	v_mfma_f32_16x16x32_bf16 v[4:7], v[180:183], v[220:223], v[4:7]
	v_mfma_f32_16x16x32_bf16 v[0:3], v[188:191], v[220:223], v[0:3]
	s_barrier
	s_add_i32 s50, s50, 2
	s_add_u32 s24, s24, 0x100
	s_addc_u32 s25, s25, 0
	s_cmp_gt_u32 s50, 13
	s_cbranch_scc0 .LBB0_778
	s_add_u32 s24, s46, 0xffffff00
	s_addc_u32 s25, s47, -1
	s_andn2_b64 vcc, exec, s[2:3]
	s_cbranch_vccnz .LBB0_781
	v_mov_b64_e32 v[0:1], 0
	s_mov_b32 s4, s16
	s_mov_b32 s10, s18
	s_mov_b64 s[12:13], s[22:23]
	s_mov_b32 s40, s45
	v_mov_b64_e32 v[2:3], 0
	v_mov_b64_e32 v[4:5], 0
	v_mov_b64_e32 v[6:7], 0
	v_mov_b64_e32 v[16:17], 0
	v_mov_b64_e32 v[18:19], 0
	v_mov_b64_e32 v[20:21], 0
	v_mov_b64_e32 v[22:23], 0
	v_mov_b64_e32 v[32:33], 0
	v_mov_b64_e32 v[34:35], 0
	v_mov_b64_e32 v[36:37], 0
	v_mov_b64_e32 v[38:39], 0
	v_mov_b64_e32 v[48:49], 0
	v_mov_b64_e32 v[50:51], 0
	v_mov_b64_e32 v[52:53], 0
	v_mov_b64_e32 v[54:55], 0
	v_mov_b64_e32 v[8:9], 0
	v_mov_b64_e32 v[10:11], 0
	v_mov_b64_e32 v[12:13], 0
	v_mov_b64_e32 v[14:15], 0
	v_mov_b64_e32 v[24:25], 0
	v_mov_b64_e32 v[26:27], 0
	v_mov_b64_e32 v[28:29], 0
	v_mov_b64_e32 v[30:31], 0
	v_mov_b64_e32 v[40:41], 0
	v_mov_b64_e32 v[42:43], 0
	v_mov_b64_e32 v[44:45], 0
	v_mov_b64_e32 v[46:47], 0
	v_mov_b64_e32 v[56:57], 0
	v_mov_b64_e32 v[58:59], 0
	v_mov_b64_e32 v[60:61], 0
	v_mov_b64_e32 v[62:63], 0
	v_mov_b64_e32 v[92:93], 0
	v_mov_b64_e32 v[94:95], 0
	v_mov_b64_e32 v[104:105], 0
	v_mov_b64_e32 v[106:107], 0
	v_mov_b64_e32 v[80:81], 0
	v_mov_b64_e32 v[82:83], 0
	v_mov_b64_e32 v[88:89], 0
	v_mov_b64_e32 v[90:91], 0
	v_mov_b64_e32 v[64:65], 0
	v_mov_b64_e32 v[66:67], 0
	v_mov_b64_e32 v[72:73], 0
	v_mov_b64_e32 v[74:75], 0
	v_mov_b64_e32 v[68:69], 0
	v_mov_b64_e32 v[70:71], 0
	v_mov_b64_e32 v[76:77], 0
	v_mov_b64_e32 v[78:79], 0
	v_mov_b64_e32 v[120:121], 0
	v_mov_b64_e32 v[122:123], 0
	v_mov_b64_e32 v[124:125], 0
	v_mov_b64_e32 v[126:127], 0
	v_mov_b64_e32 v[112:113], 0
	v_mov_b64_e32 v[114:115], 0
	v_mov_b64_e32 v[116:117], 0
	v_mov_b64_e32 v[118:119], 0
	v_mov_b64_e32 v[84:85], 0
	v_mov_b64_e32 v[86:87], 0
	v_mov_b64_e32 v[108:109], 0
	v_mov_b64_e32 v[110:111], 0
	v_mov_b64_e32 v[96:97], 0
	v_mov_b64_e32 v[98:99], 0
	v_mov_b64_e32 v[100:101], 0
	v_mov_b64_e32 v[102:103], 0
	s_branch .LBB0_782

.Lpeel942_mid:
	s_add_i32 s49, 0, 0x18000
	s_add_i32 s50, 0, 0x1c000
	v_add_u32_e32 v162, s49, v145
	v_add_u32_e32 v179, s50, v145
	ds_read_b128 v[150:153], v162
	ds_read_b128 v[154:157], v162 offset:1024
	ds_read_b128 v[158:161], v162 offset:2048
	ds_read_b128 v[162:165], v162 offset:3072
	ds_read_b128 v[166:169], v179
	ds_read_b128 v[180:183], v179 offset:1024
	ds_read_b128 v[184:187], v179 offset:2048
	ds_read_b128 v[188:191], v179 offset:3072
	s_add_u32 s26, s26, 0x40000
	s_addc_u32 s27, s27, 0
	s_mov_b32 m0, s33
	v_lshl_add_u64 v[232:233], s[26:27], 0, v[128:129]
	ds_read_b128 v[192:195], v149 offset:32768
	ds_read_b128 v[196:199], v149 offset:33792
	ds_read_b128 v[200:203], v149 offset:34816
	ds_read_b128 v[204:207], v149 offset:35840
	ds_read_b128 v[208:211], v149 offset:36864
	ds_read_b128 v[212:215], v149 offset:37888
	ds_read_b128 v[216:219], v149 offset:38912
	ds_read_b128 v[220:223], v149 offset:39936
	global_load_lds_dwordx4 v[232:233], off
	s_mov_b32 m0, s34
	v_lshl_add_u64 v[232:233], s[26:27], 0, v[132:133]
	global_load_lds_dwordx4 v[232:233], off
	s_waitcnt vmcnt(8) lgkmcnt(0)
	s_barrier
	v_mfma_f32_16x16x32_bf16 v[124:127], v[150:153], v[192:195], v[124:127]
	v_mfma_f32_16x16x32_bf16 v[120:123], v[158:161], v[192:195], v[120:123]
	v_mfma_f32_16x16x32_bf16 v[108:111], v[150:153], v[200:203], v[108:111]
	v_mfma_f32_16x16x32_bf16 v[104:107], v[158:161], v[200:203], v[104:107]
	v_mfma_f32_16x16x32_bf16 v[92:95], v[150:153], v[208:211], v[92:95]
	v_mfma_f32_16x16x32_bf16 v[88:91], v[158:161], v[208:211], v[88:91]
	v_mfma_f32_16x16x32_bf16 v[76:79], v[150:153], v[216:219], v[76:79]
	v_mfma_f32_16x16x32_bf16 v[72:75], v[158:161], v[216:219], v[72:75]
	v_mfma_f32_16x16x32_bf16 v[124:127], v[154:157], v[196:199], v[124:127]
	v_mfma_f32_16x16x32_bf16 v[120:123], v[162:165], v[196:199], v[120:123]
	v_mfma_f32_16x16x32_bf16 v[108:111], v[154:157], v[204:207], v[108:111]
	v_mfma_f32_16x16x32_bf16 v[104:107], v[162:165], v[204:207], v[104:107]
	v_mfma_f32_16x16x32_bf16 v[92:95], v[154:157], v[212:215], v[92:95]
	v_mfma_f32_16x16x32_bf16 v[88:91], v[162:165], v[212:215], v[88:91]
	v_mfma_f32_16x16x32_bf16 v[76:79], v[154:157], v[220:223], v[76:79]
	v_mfma_f32_16x16x32_bf16 v[72:75], v[162:165], v[220:223], v[72:75]
	v_mfma_f32_16x16x32_bf16 v[116:119], v[166:169], v[192:195], v[116:119]
	v_mfma_f32_16x16x32_bf16 v[112:115], v[184:187], v[192:195], v[112:115]
	v_mfma_f32_16x16x32_bf16 v[100:103], v[166:169], v[200:203], v[100:103]
	v_mfma_f32_16x16x32_bf16 v[96:99], v[184:187], v[200:203], v[96:99]
	v_mfma_f32_16x16x32_bf16 v[84:87], v[166:169], v[208:211], v[84:87]
	v_mfma_f32_16x16x32_bf16 v[80:83], v[184:187], v[208:211], v[80:83]
	v_mfma_f32_16x16x32_bf16 v[68:71], v[166:169], v[216:219], v[68:71]
	v_mfma_f32_16x16x32_bf16 v[64:67], v[184:187], v[216:219], v[64:67]
	v_mfma_f32_16x16x32_bf16 v[116:119], v[180:183], v[196:199], v[116:119]
	v_mfma_f32_16x16x32_bf16 v[112:115], v[188:191], v[196:199], v[112:115]
	v_mfma_f32_16x16x32_bf16 v[100:103], v[180:183], v[204:207], v[100:103]
	v_mfma_f32_16x16x32_bf16 v[96:99], v[188:191], v[204:207], v[96:99]
	v_mfma_f32_16x16x32_bf16 v[84:87], v[180:183], v[212:215], v[84:87]
	v_mfma_f32_16x16x32_bf16 v[80:83], v[188:191], v[212:215], v[80:83]
	v_mfma_f32_16x16x32_bf16 v[68:71], v[180:183], v[220:223], v[68:71]
	v_mfma_f32_16x16x32_bf16 v[64:67], v[188:191], v[220:223], v[64:67]
	s_barrier
	s_add_i32 s26, s49, s28
	v_lshl_add_u64 v[224:225], v[224:225], 0, s[8:9]
	s_mov_b32 m0, s26
	ds_read_b128 v[192:195], v149 offset:49152
	ds_read_b128 v[196:199], v149 offset:50176
	ds_read_b128 v[200:203], v149 offset:51200
	ds_read_b128 v[204:207], v149 offset:52224
	ds_read_b128 v[208:211], v149 offset:53248
	ds_read_b128 v[212:215], v149 offset:54272
	ds_read_b128 v[216:219], v149 offset:55296
	ds_read_b128 v[220:223], v149 offset:56320
	global_load_lds_dwordx4 v[224:225], off
	s_add_i32 m0, s26, 0x2000
	s_add_u32 s24, s24, 0x40080
	v_lshl_add_u64 v[224:225], v[226:227], 0, s[8:9]
	s_addc_u32 s25, s25, 0
	s_add_i32 s26, s50, s28
	global_load_lds_dwordx4 v[224:225], off
	s_mov_b32 m0, s26
	v_lshl_add_u64 v[224:225], s[24:25], 0, v[130:131]
	global_load_lds_dwordx4 v[224:225], off
	s_add_i32 m0, s26, 0x2000
	v_lshl_add_u64 v[224:225], s[24:25], 0, v[134:135]
	global_load_lds_dwordx4 v[224:225], off
	s_mov_b32 m0, s37
	v_lshl_add_u64 v[224:225], v[228:229], 0, s[8:9]
	global_load_lds_dwordx4 v[224:225], off
	s_mov_b32 m0, s38
	v_lshl_add_u64 v[224:225], v[230:231], 0, s[8:9]
	global_load_lds_dwordx4 v[224:225], off
	s_waitcnt vmcnt(8) lgkmcnt(0)
	s_barrier
	v_mfma_f32_16x16x32_bf16 v[60:63], v[150:153], v[192:195], v[60:63]
	v_mfma_f32_16x16x32_bf16 v[56:59], v[158:161], v[192:195], v[56:59]
	v_mfma_f32_16x16x32_bf16 v[44:47], v[150:153], v[200:203], v[44:47]
	v_mfma_f32_16x16x32_bf16 v[40:43], v[158:161], v[200:203], v[40:43]
	v_mfma_f32_16x16x32_bf16 v[28:31], v[150:153], v[208:211], v[28:31]
	v_mfma_f32_16x16x32_bf16 v[24:27], v[158:161], v[208:211], v[24:27]
	v_mfma_f32_16x16x32_bf16 v[12:15], v[150:153], v[216:219], v[12:15]
	v_mfma_f32_16x16x32_bf16 v[8:11], v[158:161], v[216:219], v[8:11]
	v_mfma_f32_16x16x32_bf16 v[60:63], v[154:157], v[196:199], v[60:63]
	v_mfma_f32_16x16x32_bf16 v[56:59], v[162:165], v[196:199], v[56:59]
	v_mfma_f32_16x16x32_bf16 v[44:47], v[154:157], v[204:207], v[44:47]
	v_mfma_f32_16x16x32_bf16 v[40:43], v[162:165], v[204:207], v[40:43]
	v_mfma_f32_16x16x32_bf16 v[28:31], v[154:157], v[212:215], v[28:31]
	v_mfma_f32_16x16x32_bf16 v[24:27], v[162:165], v[212:215], v[24:27]
	v_mfma_f32_16x16x32_bf16 v[12:15], v[154:157], v[220:223], v[12:15]
	v_mfma_f32_16x16x32_bf16 v[8:11], v[162:165], v[220:223], v[8:11]
	v_mfma_f32_16x16x32_bf16 v[52:55], v[166:169], v[192:195], v[52:55]
	v_mfma_f32_16x16x32_bf16 v[48:51], v[184:187], v[192:195], v[48:51]
	v_mfma_f32_16x16x32_bf16 v[36:39], v[166:169], v[200:203], v[36:39]
	v_mfma_f32_16x16x32_bf16 v[32:35], v[184:187], v[200:203], v[32:35]
	v_mfma_f32_16x16x32_bf16 v[20:23], v[166:169], v[208:211], v[20:23]
	v_mfma_f32_16x16x32_bf16 v[16:19], v[184:187], v[208:211], v[16:19]
	v_mfma_f32_16x16x32_bf16 v[4:7], v[166:169], v[216:219], v[4:7]
	v_mfma_f32_16x16x32_bf16 v[0:3], v[184:187], v[216:219], v[0:3]
	v_mfma_f32_16x16x32_bf16 v[52:55], v[180:183], v[196:199], v[52:55]
	v_mfma_f32_16x16x32_bf16 v[48:51], v[188:191], v[196:199], v[48:51]
	v_mfma_f32_16x16x32_bf16 v[36:39], v[180:183], v[204:207], v[36:39]
	v_mfma_f32_16x16x32_bf16 v[32:35], v[188:191], v[204:207], v[32:35]
	v_mfma_f32_16x16x32_bf16 v[20:23], v[180:183], v[212:215], v[20:23]
	v_mfma_f32_16x16x32_bf16 v[16:19], v[188:191], v[212:215], v[16:19]
	v_mfma_f32_16x16x32_bf16 v[4:7], v[180:183], v[220:223], v[4:7]
	v_mfma_f32_16x16x32_bf16 v[0:3], v[188:191], v[220:223], v[0:3]
	s_barrier
	s_add_i32 s48, s48, 2
	s_add_u32 s22, s22, 0x100
	s_addc_u32 s23, s23, 0
	s_add_u32 s46, s46, 0x100
	s_addc_u32 s47, s47, 0
	s_cmp_gt_u32 s48, 13
	s_cbranch_scc0 .LBB0_942
	s_and_b64 vcc, exec, s[10:11]
	s_cbranch_vccz .LBB0_945
	s_barrier

.LBB0_1018:
	ds_read_b128 v[152:155], v149
	ds_read_b128 v[156:159], v149 offset:1024
	ds_read_b128 v[160:163], v149 offset:2048
	ds_read_b128 v[164:167], v149 offset:3072
	ds_read_b128 v[174:177], v150
	ds_read_b128 v[178:181], v150 offset:1024
	ds_read_b128 v[182:185], v150 offset:2048
	ds_read_b128 v[186:189], v150 offset:3072
	s_add_u32 s34, s30, 0xfff50080
	s_addc_u32 s35, s31, -1
	s_cmp_eq_u32 s60, 40
	s_cselect_b32 s37, s5, s35
	s_cselect_b32 s36, s4, s34
	s_cselect_b32 s35, s29, s57
	s_cselect_b32 s34, s28, s56
	v_lshl_add_u64 v[140:141], s[30:31], 0, v[132:133]
	s_add_i32 m0, s41, 0xc000
	ds_read_b128 v[190:193], v151
	ds_read_b128 v[194:197], v151 offset:1024
	ds_read_b128 v[198:201], v151 offset:2048
	ds_read_b128 v[202:205], v151 offset:3072
	ds_read_b128 v[206:209], v151 offset:4096
	ds_read_b128 v[210:213], v151 offset:5120
	ds_read_b128 v[214:217], v151 offset:6144
	ds_read_b128 v[218:221], v151 offset:7168
	global_load_lds_dwordx4 v[140:141], off
	s_add_i32 m0, s41, 0xe000
	v_lshl_add_u64 v[140:141], s[30:31], 0, v[134:135]
	global_load_lds_dwordx4 v[140:141], off
	s_waitcnt vmcnt(8) lgkmcnt(0)
	s_barrier
	v_mfma_f32_16x16x32_bf16 v[124:127], v[152:155], v[190:193], v[124:127]
	v_mfma_f32_16x16x32_bf16 v[120:123], v[160:163], v[190:193], v[120:123]
	v_mfma_f32_16x16x32_bf16 v[112:115], v[152:155], v[198:201], v[112:115]
	v_mfma_f32_16x16x32_bf16 v[108:111], v[160:163], v[198:201], v[108:111]
	v_mfma_f32_16x16x32_bf16 v[96:99], v[152:155], v[206:209], v[96:99]
	v_mfma_f32_16x16x32_bf16 v[92:95], v[160:163], v[206:209], v[92:95]
	v_mfma_f32_16x16x32_bf16 v[80:83], v[152:155], v[214:217], v[80:83]
	v_mfma_f32_16x16x32_bf16 v[76:79], v[160:163], v[214:217], v[76:79]
	v_mfma_f32_16x16x32_bf16 v[124:127], v[156:159], v[194:197], v[124:127]
	v_mfma_f32_16x16x32_bf16 v[120:123], v[164:167], v[194:197], v[120:123]
	v_mfma_f32_16x16x32_bf16 v[112:115], v[156:159], v[202:205], v[112:115]
	v_mfma_f32_16x16x32_bf16 v[108:111], v[164:167], v[202:205], v[108:111]
	v_mfma_f32_16x16x32_bf16 v[96:99], v[156:159], v[210:213], v[96:99]
	v_mfma_f32_16x16x32_bf16 v[92:95], v[164:167], v[210:213], v[92:95]
	v_mfma_f32_16x16x32_bf16 v[80:83], v[156:159], v[218:221], v[80:83]
	v_mfma_f32_16x16x32_bf16 v[76:79], v[164:167], v[218:221], v[76:79]
	v_mfma_f32_16x16x32_bf16 v[116:119], v[174:177], v[190:193], v[116:119]
	v_mfma_f32_16x16x32_bf16 v[104:107], v[182:185], v[190:193], v[104:107]
	v_mfma_f32_16x16x32_bf16 v[100:103], v[174:177], v[198:201], v[100:103]
	v_mfma_f32_16x16x32_bf16 v[88:91], v[182:185], v[198:201], v[88:91]
	v_mfma_f32_16x16x32_bf16 v[84:87], v[174:177], v[206:209], v[84:87]
	v_mfma_f32_16x16x32_bf16 v[72:75], v[182:185], v[206:209], v[72:75]
	v_mfma_f32_16x16x32_bf16 v[68:71], v[174:177], v[214:217], v[68:71]
	v_mfma_f32_16x16x32_bf16 v[64:67], v[182:185], v[214:217], v[64:67]
	v_mfma_f32_16x16x32_bf16 v[116:119], v[178:181], v[194:197], v[116:119]
	v_mfma_f32_16x16x32_bf16 v[104:107], v[186:189], v[194:197], v[104:107]
	v_mfma_f32_16x16x32_bf16 v[100:103], v[178:181], v[202:205], v[100:103]
	v_mfma_f32_16x16x32_bf16 v[88:91], v[186:189], v[202:205], v[88:91]
	v_mfma_f32_16x16x32_bf16 v[84:87], v[178:181], v[210:213], v[84:87]
	v_mfma_f32_16x16x32_bf16 v[72:75], v[186:189], v[210:213], v[72:75]
	v_mfma_f32_16x16x32_bf16 v[68:71], v[178:181], v[218:221], v[68:71]
	v_mfma_f32_16x16x32_bf16 v[64:67], v[186:189], v[218:221], v[64:67]
	s_barrier
	s_add_i32 s61, s50, s40
	v_lshl_add_u64 v[140:141], s[34:35], 0, v[128:129]
	s_mov_b32 m0, s61
	ds_read_b128 v[190:193], v151 offset:16384
	ds_read_b128 v[194:197], v151 offset:17408
	ds_read_b128 v[198:201], v151 offset:18432
	ds_read_b128 v[202:205], v151 offset:19456
	ds_read_b128 v[206:209], v151 offset:20480
	ds_read_b128 v[210:213], v151 offset:21504
	ds_read_b128 v[214:217], v151 offset:22528
	ds_read_b128 v[218:221], v151 offset:23552
	global_load_lds_dwordx4 v[140:141], off
	s_add_i32 m0, s61, 0x2000
	s_add_u32 s62, s34, 0xb0000
	v_lshl_add_u64 v[168:169], s[34:35], 0, v[130:131]
	s_addc_u32 s63, s35, 0
	s_add_i32 s61, s51, s40
	global_load_lds_dwordx4 v[168:169], off
	v_lshl_add_u64 v[222:223], s[62:63], 0, v[128:129]
	s_mov_b32 m0, s61
	v_lshl_add_u64 v[224:225], s[36:37], 0, v[130:131]
	global_load_lds_dwordx4 v[222:223], off
	s_add_i32 m0, s61, 0x2000
	v_lshl_add_u64 v[222:223], s[62:63], 0, v[130:131]
	global_load_lds_dwordx4 v[222:223], off
	s_mov_b32 m0, s41
	v_lshl_add_u64 v[222:223], s[36:37], 0, v[128:129]
	global_load_lds_dwordx4 v[222:223], off
	s_mov_b32 m0, s42
	s_nop 0
	global_load_lds_dwordx4 v[224:225], off
	s_waitcnt vmcnt(8) lgkmcnt(0)
	s_barrier
	v_mfma_f32_16x16x32_bf16 v[60:63], v[152:155], v[190:193], v[60:63]
	v_mfma_f32_16x16x32_bf16 v[56:59], v[160:163], v[190:193], v[56:59]
	v_mfma_f32_16x16x32_bf16 v[48:51], v[152:155], v[198:201], v[48:51]
	v_mfma_f32_16x16x32_bf16 v[44:47], v[160:163], v[198:201], v[44:47]
	v_mfma_f32_16x16x32_bf16 v[32:35], v[152:155], v[206:209], v[32:35]
	v_mfma_f32_16x16x32_bf16 v[28:31], v[160:163], v[206:209], v[28:31]
	v_mfma_f32_16x16x32_bf16 v[16:19], v[152:155], v[214:217], v[16:19]
	v_mfma_f32_16x16x32_bf16 v[8:11], v[160:163], v[214:217], v[8:11]
	v_mfma_f32_16x16x32_bf16 v[60:63], v[156:159], v[194:197], v[60:63]
	v_mfma_f32_16x16x32_bf16 v[56:59], v[164:167], v[194:197], v[56:59]
	v_mfma_f32_16x16x32_bf16 v[48:51], v[156:159], v[202:205], v[48:51]
	v_mfma_f32_16x16x32_bf16 v[44:47], v[164:167], v[202:205], v[44:47]
	v_mfma_f32_16x16x32_bf16 v[32:35], v[156:159], v[210:213], v[32:35]
	v_mfma_f32_16x16x32_bf16 v[28:31], v[164:167], v[210:213], v[28:31]
	v_mfma_f32_16x16x32_bf16 v[16:19], v[156:159], v[218:221], v[16:19]
	v_mfma_f32_16x16x32_bf16 v[8:11], v[164:167], v[218:221], v[8:11]
	v_mfma_f32_16x16x32_bf16 v[52:55], v[174:177], v[190:193], v[52:55]
	v_mfma_f32_16x16x32_bf16 v[40:43], v[182:185], v[190:193], v[40:43]
	v_mfma_f32_16x16x32_bf16 v[36:39], v[174:177], v[198:201], v[36:39]
	v_mfma_f32_16x16x32_bf16 v[24:27], v[182:185], v[198:201], v[24:27]
	v_mfma_f32_16x16x32_bf16 v[20:23], v[174:177], v[206:209], v[20:23]
	v_mfma_f32_16x16x32_bf16 v[12:15], v[182:185], v[206:209], v[12:15]
	v_mfma_f32_16x16x32_bf16 v[4:7], v[174:177], v[214:217], v[4:7]
	v_mfma_f32_16x16x32_bf16 v[0:3], v[182:185], v[214:217], v[0:3]
	v_mfma_f32_16x16x32_bf16 v[52:55], v[178:181], v[194:197], v[52:55]
	v_mfma_f32_16x16x32_bf16 v[40:43], v[186:189], v[194:197], v[40:43]
	v_mfma_f32_16x16x32_bf16 v[36:39], v[178:181], v[202:205], v[36:39]
	v_mfma_f32_16x16x32_bf16 v[24:27], v[186:189], v[202:205], v[24:27]
	v_mfma_f32_16x16x32_bf16 v[20:23], v[178:181], v[210:213], v[20:23]
	v_mfma_f32_16x16x32_bf16 v[12:15], v[186:189], v[210:213], v[12:15]
	v_mfma_f32_16x16x32_bf16 v[4:7], v[178:181], v[218:221], v[4:7]
	v_mfma_f32_16x16x32_bf16 v[0:3], v[186:189], v[218:221], v[0:3]
	s_barrier
	s_add_i32 s61, 0, 0x18000
	s_add_i32 s62, 0, 0x1c000
	v_add_u32_e32 v164, s61, v147
	v_add_u32_e32 v186, s62, v147
	ds_read_b128 v[152:155], v164
	ds_read_b128 v[156:159], v164 offset:1024
	ds_read_b128 v[160:163], v164 offset:2048
	ds_read_b128 v[164:167], v164 offset:3072
	ds_read_b128 v[174:177], v186
	ds_read_b128 v[178:181], v186 offset:1024
	ds_read_b128 v[182:185], v186 offset:2048
	ds_read_b128 v[186:189], v186 offset:3072
	s_add_u32 s36, s36, 0xb0000
	s_addc_u32 s37, s37, 0
	s_mov_b32 m0, s43
	v_lshl_add_u64 v[226:227], s[36:37], 0, v[128:129]
	ds_read_b128 v[190:193], v151 offset:32768
	ds_read_b128 v[194:197], v151 offset:33792
	ds_read_b128 v[198:201], v151 offset:34816
	ds_read_b128 v[202:205], v151 offset:35840
	ds_read_b128 v[206:209], v151 offset:36864
	ds_read_b128 v[210:213], v151 offset:37888
	ds_read_b128 v[214:217], v151 offset:38912
	ds_read_b128 v[218:221], v151 offset:39936
	global_load_lds_dwordx4 v[226:227], off
	s_mov_b32 m0, s44
	v_lshl_add_u64 v[226:227], s[36:37], 0, v[130:131]
	global_load_lds_dwordx4 v[226:227], off
	s_waitcnt vmcnt(8) lgkmcnt(0)
	s_barrier
	v_mfma_f32_16x16x32_bf16 v[124:127], v[152:155], v[190:193], v[124:127]
	v_mfma_f32_16x16x32_bf16 v[120:123], v[160:163], v[190:193], v[120:123]
	v_mfma_f32_16x16x32_bf16 v[112:115], v[152:155], v[198:201], v[112:115]
	v_mfma_f32_16x16x32_bf16 v[108:111], v[160:163], v[198:201], v[108:111]
	v_mfma_f32_16x16x32_bf16 v[96:99], v[152:155], v[206:209], v[96:99]
	v_mfma_f32_16x16x32_bf16 v[92:95], v[160:163], v[206:209], v[92:95]
	v_mfma_f32_16x16x32_bf16 v[80:83], v[152:155], v[214:217], v[80:83]
	v_mfma_f32_16x16x32_bf16 v[76:79], v[160:163], v[214:217], v[76:79]
	v_mfma_f32_16x16x32_bf16 v[124:127], v[156:159], v[194:197], v[124:127]
	v_mfma_f32_16x16x32_bf16 v[120:123], v[164:167], v[194:197], v[120:123]
	v_mfma_f32_16x16x32_bf16 v[112:115], v[156:159], v[202:205], v[112:115]
	v_mfma_f32_16x16x32_bf16 v[108:111], v[164:167], v[202:205], v[108:111]
	v_mfma_f32_16x16x32_bf16 v[96:99], v[156:159], v[210:213], v[96:99]
	v_mfma_f32_16x16x32_bf16 v[92:95], v[164:167], v[210:213], v[92:95]
	v_mfma_f32_16x16x32_bf16 v[80:83], v[156:159], v[218:221], v[80:83]
	v_mfma_f32_16x16x32_bf16 v[76:79], v[164:167], v[218:221], v[76:79]
	v_mfma_f32_16x16x32_bf16 v[116:119], v[174:177], v[190:193], v[116:119]
	v_mfma_f32_16x16x32_bf16 v[104:107], v[182:185], v[190:193], v[104:107]
	v_mfma_f32_16x16x32_bf16 v[100:103], v[174:177], v[198:201], v[100:103]
	v_mfma_f32_16x16x32_bf16 v[88:91], v[182:185], v[198:201], v[88:91]
	v_mfma_f32_16x16x32_bf16 v[84:87], v[174:177], v[206:209], v[84:87]
	v_mfma_f32_16x16x32_bf16 v[72:75], v[182:185], v[206:209], v[72:75]
	v_mfma_f32_16x16x32_bf16 v[68:71], v[174:177], v[214:217], v[68:71]
	v_mfma_f32_16x16x32_bf16 v[64:67], v[182:185], v[214:217], v[64:67]
	v_mfma_f32_16x16x32_bf16 v[116:119], v[178:181], v[194:197], v[116:119]
	v_mfma_f32_16x16x32_bf16 v[104:107], v[186:189], v[194:197], v[104:107]
	v_mfma_f32_16x16x32_bf16 v[100:103], v[178:181], v[202:205], v[100:103]
	v_mfma_f32_16x16x32_bf16 v[88:91], v[186:189], v[202:205], v[88:91]
	v_mfma_f32_16x16x32_bf16 v[84:87], v[178:181], v[210:213], v[84:87]
	v_mfma_f32_16x16x32_bf16 v[72:75], v[186:189], v[210:213], v[72:75]
	v_mfma_f32_16x16x32_bf16 v[68:71], v[178:181], v[218:221], v[68:71]
	v_mfma_f32_16x16x32_bf16 v[64:67], v[186:189], v[218:221], v[64:67]
	s_barrier
	s_add_i32 s36, s61, s40
	v_lshl_add_u64 v[140:141], v[140:141], 0, s[16:17]
	s_mov_b32 m0, s36
	ds_read_b128 v[190:193], v151 offset:49152
	ds_read_b128 v[194:197], v151 offset:50176
	ds_read_b128 v[198:201], v151 offset:51200
	ds_read_b128 v[202:205], v151 offset:52224
	ds_read_b128 v[206:209], v151 offset:53248
	ds_read_b128 v[210:213], v151 offset:54272
	ds_read_b128 v[214:217], v151 offset:55296
	ds_read_b128 v[218:221], v151 offset:56320
	global_load_lds_dwordx4 v[140:141], off
	s_add_i32 m0, s36, 0x2000
	s_add_u32 s34, s34, 0xb0080
	v_lshl_add_u64 v[140:141], v[168:169], 0, s[16:17]
	s_addc_u32 s35, s35, 0
	s_add_i32 s36, s62, s40
	global_load_lds_dwordx4 v[140:141], off
	s_mov_b32 m0, s36
	v_lshl_add_u64 v[140:141], s[34:35], 0, v[128:129]
	global_load_lds_dwordx4 v[140:141], off
	s_add_i32 m0, s36, 0x2000
	v_lshl_add_u64 v[140:141], s[34:35], 0, v[130:131]
	global_load_lds_dwordx4 v[140:141], off
	s_mov_b32 m0, s47
	v_lshl_add_u64 v[140:141], v[222:223], 0, s[16:17]
	global_load_lds_dwordx4 v[140:141], off
	s_mov_b32 m0, s48
	v_lshl_add_u64 v[140:141], v[224:225], 0, s[16:17]
	global_load_lds_dwordx4 v[140:141], off
	s_waitcnt vmcnt(8) lgkmcnt(0)
	s_barrier
	v_mfma_f32_16x16x32_bf16 v[60:63], v[152:155], v[190:193], v[60:63]
	v_mfma_f32_16x16x32_bf16 v[56:59], v[160:163], v[190:193], v[56:59]
	v_mfma_f32_16x16x32_bf16 v[48:51], v[152:155], v[198:201], v[48:51]
	v_mfma_f32_16x16x32_bf16 v[44:47], v[160:163], v[198:201], v[44:47]
	v_mfma_f32_16x16x32_bf16 v[32:35], v[152:155], v[206:209], v[32:35]
	v_mfma_f32_16x16x32_bf16 v[28:31], v[160:163], v[206:209], v[28:31]
	v_mfma_f32_16x16x32_bf16 v[16:19], v[152:155], v[214:217], v[16:19]
	v_mfma_f32_16x16x32_bf16 v[8:11], v[160:163], v[214:217], v[8:11]
	v_mfma_f32_16x16x32_bf16 v[60:63], v[156:159], v[194:197], v[60:63]
	v_mfma_f32_16x16x32_bf16 v[56:59], v[164:167], v[194:197], v[56:59]
	v_mfma_f32_16x16x32_bf16 v[48:51], v[156:159], v[202:205], v[48:51]
	v_mfma_f32_16x16x32_bf16 v[44:47], v[164:167], v[202:205], v[44:47]
	v_mfma_f32_16x16x32_bf16 v[32:35], v[156:159], v[210:213], v[32:35]
	v_mfma_f32_16x16x32_bf16 v[28:31], v[164:167], v[210:213], v[28:31]
	v_mfma_f32_16x16x32_bf16 v[16:19], v[156:159], v[218:221], v[16:19]
	v_mfma_f32_16x16x32_bf16 v[8:11], v[164:167], v[218:221], v[8:11]
	v_mfma_f32_16x16x32_bf16 v[52:55], v[174:177], v[190:193], v[52:55]
	v_mfma_f32_16x16x32_bf16 v[40:43], v[182:185], v[190:193], v[40:43]
	v_mfma_f32_16x16x32_bf16 v[36:39], v[174:177], v[198:201], v[36:39]
	v_mfma_f32_16x16x32_bf16 v[24:27], v[182:185], v[198:201], v[24:27]
	v_mfma_f32_16x16x32_bf16 v[20:23], v[174:177], v[206:209], v[20:23]
	v_mfma_f32_16x16x32_bf16 v[12:15], v[182:185], v[206:209], v[12:15]
	v_mfma_f32_16x16x32_bf16 v[4:7], v[174:177], v[214:217], v[4:7]
	v_mfma_f32_16x16x32_bf16 v[0:3], v[182:185], v[214:217], v[0:3]
	v_mfma_f32_16x16x32_bf16 v[52:55], v[178:181], v[194:197], v[52:55]
	v_mfma_f32_16x16x32_bf16 v[40:43], v[186:189], v[194:197], v[40:43]
	v_mfma_f32_16x16x32_bf16 v[36:39], v[178:181], v[202:205], v[36:39]
	v_mfma_f32_16x16x32_bf16 v[24:27], v[186:189], v[202:205], v[24:27]
	v_mfma_f32_16x16x32_bf16 v[20:23], v[178:181], v[210:213], v[20:23]
	v_mfma_f32_16x16x32_bf16 v[12:15], v[186:189], v[210:213], v[12:15]
	v_mfma_f32_16x16x32_bf16 v[4:7], v[178:181], v[218:221], v[4:7]
	v_mfma_f32_16x16x32_bf16 v[0:3], v[186:189], v[218:221], v[0:3]
	s_barrier
	s_add_i32 s60, s60, 2
	s_add_u32 s30, s30, 0x100
	s_addc_u32 s31, s31, 0
	s_add_u32 s56, s56, 0x100
	s_addc_u32 s57, s57, 0
	s_cmp_gt_u32 s60, 41
	s_cbranch_scc0 .LBB0_1018
	s_and_b64 vcc, exec, s[18:19]
	s_cbranch_vccz .LBB0_1021
	s_barrier

.LBB0_1042:
	v_add_u32_e32 v147, s39, v146
	ds_read_b128 v[148:151], v147
	ds_read_b128 v[152:155], v147 offset:1024
	ds_read_b128 v[156:159], v147 offset:2048
	ds_read_b128 v[164:167], v147 offset:3072
	v_add_u32_e32 v147, s40, v146
	s_add_u32 s20, s12, s18
	ds_read_b128 v[174:177], v147
	ds_read_b128 v[178:181], v147 offset:1024
	ds_read_b128 v[182:185], v147 offset:2048
	ds_read_b128 v[186:189], v147 offset:3072
	s_addc_u32 s21, s13, s19
	s_add_u32 s20, s20, 0x100
	s_addc_u32 s21, s21, 0
	s_add_u32 s47, s44, s18
	s_addc_u32 s48, s45, s19
	s_cmpk_eq_i32 s18, 0x1500
	s_cselect_b32 s23, s17, s21
	s_cselect_b32 s22, s16, s20
	s_cselect_b32 s21, s5, s48
	s_cselect_b32 s20, s4, s47
	v_lshl_add_u64 v[160:161], v[140:141], 0, s[18:19]
	s_add_i32 m0, s29, 0xc000
	ds_read_b128 v[190:193], v144
	ds_read_b128 v[194:197], v144 offset:1024
	ds_read_b128 v[198:201], v144 offset:2048
	ds_read_b128 v[202:205], v144 offset:3072
	ds_read_b128 v[206:209], v144 offset:4096
	ds_read_b128 v[210:213], v144 offset:5120
	ds_read_b128 v[214:217], v144 offset:6144
	ds_read_b128 v[218:221], v144 offset:7168
	global_load_lds_dwordx4 v[160:161], off
	s_add_i32 m0, s29, 0xe000
	v_lshl_add_u64 v[160:161], v[142:143], 0, s[18:19]
	global_load_lds_dwordx4 v[160:161], off
	s_waitcnt vmcnt(8) lgkmcnt(0)
	s_barrier
	v_mfma_f32_16x16x32_bf16 v[124:127], v[148:151], v[190:193], v[124:127]
	v_mfma_f32_16x16x32_bf16 v[120:123], v[156:159], v[190:193], v[120:123]
	v_mfma_f32_16x16x32_bf16 v[116:119], v[148:151], v[198:201], v[116:119]
	v_mfma_f32_16x16x32_bf16 v[100:103], v[156:159], v[198:201], v[100:103]
	v_mfma_f32_16x16x32_bf16 v[104:107], v[148:151], v[206:209], v[104:107]
	v_mfma_f32_16x16x32_bf16 v[92:95], v[156:159], v[206:209], v[92:95]
	v_mfma_f32_16x16x32_bf16 v[96:99], v[148:151], v[214:217], v[96:99]
	v_mfma_f32_16x16x32_bf16 v[76:79], v[156:159], v[214:217], v[76:79]
	v_mfma_f32_16x16x32_bf16 v[124:127], v[152:155], v[194:197], v[124:127]
	v_mfma_f32_16x16x32_bf16 v[120:123], v[164:167], v[194:197], v[120:123]
	v_mfma_f32_16x16x32_bf16 v[116:119], v[152:155], v[202:205], v[116:119]
	v_mfma_f32_16x16x32_bf16 v[100:103], v[164:167], v[202:205], v[100:103]
	v_mfma_f32_16x16x32_bf16 v[104:107], v[152:155], v[210:213], v[104:107]
	v_mfma_f32_16x16x32_bf16 v[92:95], v[164:167], v[210:213], v[92:95]
	v_mfma_f32_16x16x32_bf16 v[96:99], v[152:155], v[218:221], v[96:99]
	v_mfma_f32_16x16x32_bf16 v[76:79], v[164:167], v[218:221], v[76:79]
	v_mfma_f32_16x16x32_bf16 v[112:115], v[174:177], v[190:193], v[112:115]
	v_mfma_f32_16x16x32_bf16 v[108:111], v[182:185], v[190:193], v[108:111]
	v_mfma_f32_16x16x32_bf16 v[88:91], v[174:177], v[198:201], v[88:91]
	v_mfma_f32_16x16x32_bf16 v[80:83], v[182:185], v[198:201], v[80:83]
	v_mfma_f32_16x16x32_bf16 v[84:87], v[174:177], v[206:209], v[84:87]
	v_mfma_f32_16x16x32_bf16 v[72:75], v[182:185], v[206:209], v[72:75]
	v_mfma_f32_16x16x32_bf16 v[68:71], v[174:177], v[214:217], v[68:71]
	v_mfma_f32_16x16x32_bf16 v[64:67], v[182:185], v[214:217], v[64:67]
	v_mfma_f32_16x16x32_bf16 v[112:115], v[178:181], v[194:197], v[112:115]
	v_mfma_f32_16x16x32_bf16 v[108:111], v[186:189], v[194:197], v[108:111]
	v_mfma_f32_16x16x32_bf16 v[88:91], v[178:181], v[202:205], v[88:91]
	v_mfma_f32_16x16x32_bf16 v[80:83], v[186:189], v[202:205], v[80:83]
	v_mfma_f32_16x16x32_bf16 v[84:87], v[178:181], v[210:213], v[84:87]
	v_mfma_f32_16x16x32_bf16 v[72:75], v[186:189], v[210:213], v[72:75]
	v_mfma_f32_16x16x32_bf16 v[68:71], v[178:181], v[218:221], v[68:71]
	v_mfma_f32_16x16x32_bf16 v[64:67], v[186:189], v[218:221], v[64:67]
	s_barrier
	s_add_i32 s47, s39, s28
	v_lshl_add_u64 v[160:161], s[20:21], 0, v[128:129]
	s_mov_b32 m0, s47
	ds_read_b128 v[190:193], v144 offset:16384
	ds_read_b128 v[194:197], v144 offset:17408
	ds_read_b128 v[198:201], v144 offset:18432
	ds_read_b128 v[202:205], v144 offset:19456
	ds_read_b128 v[206:209], v144 offset:20480
	ds_read_b128 v[210:213], v144 offset:21504
	ds_read_b128 v[214:217], v144 offset:22528
	ds_read_b128 v[218:221], v144 offset:23552
	global_load_lds_dwordx4 v[160:161], off
	s_add_i32 m0, s47, 0x2000
	s_add_u32 s48, s20, 0xb0000
	v_lshl_add_u64 v[168:169], s[20:21], 0, v[130:131]
	s_addc_u32 s49, s21, 0
	s_add_i32 s47, s40, s28
	global_load_lds_dwordx4 v[168:169], off
	v_lshl_add_u64 v[222:223], s[48:49], 0, v[128:129]
	s_mov_b32 m0, s47
	v_lshl_add_u64 v[224:225], s[22:23], 0, v[130:131]
	global_load_lds_dwordx4 v[222:223], off
	s_add_i32 m0, s47, 0x2000
	v_lshl_add_u64 v[222:223], s[48:49], 0, v[130:131]
	global_load_lds_dwordx4 v[222:223], off
	s_mov_b32 m0, s29
	v_lshl_add_u64 v[222:223], s[22:23], 0, v[128:129]
	global_load_lds_dwordx4 v[222:223], off
	s_mov_b32 m0, s30
	s_nop 0
	global_load_lds_dwordx4 v[224:225], off
	s_waitcnt vmcnt(8) lgkmcnt(0)
	s_barrier
	v_mfma_f32_16x16x32_bf16 v[60:63], v[148:151], v[190:193], v[60:63]
	v_mfma_f32_16x16x32_bf16 v[56:59], v[156:159], v[190:193], v[56:59]
	v_mfma_f32_16x16x32_bf16 v[44:47], v[148:151], v[198:201], v[44:47]
	v_mfma_f32_16x16x32_bf16 v[40:43], v[156:159], v[198:201], v[40:43]
	v_mfma_f32_16x16x32_bf16 v[28:31], v[148:151], v[206:209], v[28:31]
	v_mfma_f32_16x16x32_bf16 v[24:27], v[156:159], v[206:209], v[24:27]
	v_mfma_f32_16x16x32_bf16 v[12:15], v[148:151], v[214:217], v[12:15]
	v_mfma_f32_16x16x32_bf16 v[8:11], v[156:159], v[214:217], v[8:11]
	v_mfma_f32_16x16x32_bf16 v[60:63], v[152:155], v[194:197], v[60:63]
	v_mfma_f32_16x16x32_bf16 v[56:59], v[164:167], v[194:197], v[56:59]
	v_mfma_f32_16x16x32_bf16 v[44:47], v[152:155], v[202:205], v[44:47]
	v_mfma_f32_16x16x32_bf16 v[40:43], v[164:167], v[202:205], v[40:43]
	v_mfma_f32_16x16x32_bf16 v[28:31], v[152:155], v[210:213], v[28:31]
	v_mfma_f32_16x16x32_bf16 v[24:27], v[164:167], v[210:213], v[24:27]
	v_mfma_f32_16x16x32_bf16 v[12:15], v[152:155], v[218:221], v[12:15]
	v_mfma_f32_16x16x32_bf16 v[8:11], v[164:167], v[218:221], v[8:11]
	v_mfma_f32_16x16x32_bf16 v[52:55], v[174:177], v[190:193], v[52:55]
	v_mfma_f32_16x16x32_bf16 v[48:51], v[182:185], v[190:193], v[48:51]
	v_mfma_f32_16x16x32_bf16 v[36:39], v[174:177], v[198:201], v[36:39]
	v_mfma_f32_16x16x32_bf16 v[32:35], v[182:185], v[198:201], v[32:35]
	v_mfma_f32_16x16x32_bf16 v[20:23], v[174:177], v[206:209], v[20:23]
	v_mfma_f32_16x16x32_bf16 v[16:19], v[182:185], v[206:209], v[16:19]
	v_mfma_f32_16x16x32_bf16 v[4:7], v[174:177], v[214:217], v[4:7]
	v_mfma_f32_16x16x32_bf16 v[0:3], v[182:185], v[214:217], v[0:3]
	v_mfma_f32_16x16x32_bf16 v[52:55], v[178:181], v[194:197], v[52:55]
	v_mfma_f32_16x16x32_bf16 v[48:51], v[186:189], v[194:197], v[48:51]
	v_mfma_f32_16x16x32_bf16 v[36:39], v[178:181], v[202:205], v[36:39]
	v_mfma_f32_16x16x32_bf16 v[32:35], v[186:189], v[202:205], v[32:35]
	v_mfma_f32_16x16x32_bf16 v[20:23], v[178:181], v[210:213], v[20:23]
	v_mfma_f32_16x16x32_bf16 v[16:19], v[186:189], v[210:213], v[16:19]
	v_mfma_f32_16x16x32_bf16 v[4:7], v[178:181], v[218:221], v[4:7]
	v_mfma_f32_16x16x32_bf16 v[0:3], v[186:189], v[218:221], v[0:3]
	s_barrier
	s_add_i32 s47, 0, 0x18000
	v_add_u32_e32 v147, s47, v146
	s_add_i32 s48, 0, 0x1c000
	ds_read_b128 v[148:151], v147
	ds_read_b128 v[152:155], v147 offset:1024
	ds_read_b128 v[156:159], v147 offset:2048
	ds_read_b128 v[164:167], v147 offset:3072
	v_add_u32_e32 v147, s48, v146
	ds_read_b128 v[174:177], v147
	ds_read_b128 v[178:181], v147 offset:1024
	ds_read_b128 v[182:185], v147 offset:2048
	ds_read_b128 v[186:189], v147 offset:3072
	s_add_u32 s22, s22, 0xb0000
	s_addc_u32 s23, s23, 0
	s_mov_b32 m0, s31
	v_lshl_add_u64 v[226:227], s[22:23], 0, v[128:129]
	ds_read_b128 v[190:193], v144 offset:32768
	ds_read_b128 v[194:197], v144 offset:33792
	ds_read_b128 v[198:201], v144 offset:34816
	ds_read_b128 v[202:205], v144 offset:35840
	ds_read_b128 v[206:209], v144 offset:36864
	ds_read_b128 v[210:213], v144 offset:37888
	ds_read_b128 v[214:217], v144 offset:38912
	ds_read_b128 v[218:221], v144 offset:39936
	global_load_lds_dwordx4 v[226:227], off
	s_mov_b32 m0, s34
	v_lshl_add_u64 v[226:227], s[22:23], 0, v[130:131]
	global_load_lds_dwordx4 v[226:227], off
	s_waitcnt vmcnt(8) lgkmcnt(0)
	s_barrier
	v_mfma_f32_16x16x32_bf16 v[124:127], v[148:151], v[190:193], v[124:127]
	v_mfma_f32_16x16x32_bf16 v[120:123], v[156:159], v[190:193], v[120:123]
	v_mfma_f32_16x16x32_bf16 v[116:119], v[148:151], v[198:201], v[116:119]
	v_mfma_f32_16x16x32_bf16 v[100:103], v[156:159], v[198:201], v[100:103]
	v_mfma_f32_16x16x32_bf16 v[104:107], v[148:151], v[206:209], v[104:107]
	v_mfma_f32_16x16x32_bf16 v[92:95], v[156:159], v[206:209], v[92:95]
	v_mfma_f32_16x16x32_bf16 v[96:99], v[148:151], v[214:217], v[96:99]
	v_mfma_f32_16x16x32_bf16 v[76:79], v[156:159], v[214:217], v[76:79]
	v_mfma_f32_16x16x32_bf16 v[124:127], v[152:155], v[194:197], v[124:127]
	v_mfma_f32_16x16x32_bf16 v[120:123], v[164:167], v[194:197], v[120:123]
	v_mfma_f32_16x16x32_bf16 v[116:119], v[152:155], v[202:205], v[116:119]
	v_mfma_f32_16x16x32_bf16 v[100:103], v[164:167], v[202:205], v[100:103]
	v_mfma_f32_16x16x32_bf16 v[104:107], v[152:155], v[210:213], v[104:107]
	v_mfma_f32_16x16x32_bf16 v[92:95], v[164:167], v[210:213], v[92:95]
	v_mfma_f32_16x16x32_bf16 v[96:99], v[152:155], v[218:221], v[96:99]
	v_mfma_f32_16x16x32_bf16 v[76:79], v[164:167], v[218:221], v[76:79]
	v_mfma_f32_16x16x32_bf16 v[112:115], v[174:177], v[190:193], v[112:115]
	v_mfma_f32_16x16x32_bf16 v[108:111], v[182:185], v[190:193], v[108:111]
	v_mfma_f32_16x16x32_bf16 v[88:91], v[174:177], v[198:201], v[88:91]
	v_mfma_f32_16x16x32_bf16 v[80:83], v[182:185], v[198:201], v[80:83]
	v_mfma_f32_16x16x32_bf16 v[84:87], v[174:177], v[206:209], v[84:87]
	v_mfma_f32_16x16x32_bf16 v[72:75], v[182:185], v[206:209], v[72:75]
	v_mfma_f32_16x16x32_bf16 v[68:71], v[174:177], v[214:217], v[68:71]
	v_mfma_f32_16x16x32_bf16 v[64:67], v[182:185], v[214:217], v[64:67]
	v_mfma_f32_16x16x32_bf16 v[112:115], v[178:181], v[194:197], v[112:115]
	v_mfma_f32_16x16x32_bf16 v[108:111], v[186:189], v[194:197], v[108:111]
	v_mfma_f32_16x16x32_bf16 v[88:91], v[178:181], v[202:205], v[88:91]
	v_mfma_f32_16x16x32_bf16 v[80:83], v[186:189], v[202:205], v[80:83]
	v_mfma_f32_16x16x32_bf16 v[84:87], v[178:181], v[210:213], v[84:87]
	v_mfma_f32_16x16x32_bf16 v[72:75], v[186:189], v[210:213], v[72:75]
	v_mfma_f32_16x16x32_bf16 v[68:71], v[178:181], v[218:221], v[68:71]
	v_mfma_f32_16x16x32_bf16 v[64:67], v[186:189], v[218:221], v[64:67]
	s_barrier
	s_add_i32 s22, s47, s28
	v_lshl_add_u64 v[160:161], v[160:161], 0, s[14:15]
	s_mov_b32 m0, s22
	ds_read_b128 v[190:193], v144 offset:49152
	ds_read_b128 v[194:197], v144 offset:50176
	ds_read_b128 v[198:201], v144 offset:51200
	ds_read_b128 v[202:205], v144 offset:52224
	ds_read_b128 v[206:209], v144 offset:53248
	ds_read_b128 v[210:213], v144 offset:54272
	ds_read_b128 v[214:217], v144 offset:55296
	ds_read_b128 v[218:221], v144 offset:56320
	global_load_lds_dwordx4 v[160:161], off
	s_add_i32 m0, s22, 0x2000
	s_add_u32 s20, s20, 0xb0080
	v_lshl_add_u64 v[160:161], v[168:169], 0, s[14:15]
	s_addc_u32 s21, s21, 0
	s_add_i32 s22, s48, s28
	global_load_lds_dwordx4 v[160:161], off
	s_mov_b32 m0, s22
	v_lshl_add_u64 v[160:161], s[20:21], 0, v[128:129]
	global_load_lds_dwordx4 v[160:161], off
	s_add_i32 m0, s22, 0x2000
	v_lshl_add_u64 v[160:161], s[20:21], 0, v[130:131]
	global_load_lds_dwordx4 v[160:161], off
	s_mov_b32 m0, s37
	v_lshl_add_u64 v[160:161], v[222:223], 0, s[14:15]
	global_load_lds_dwordx4 v[160:161], off
	s_mov_b32 m0, s38
	v_lshl_add_u64 v[160:161], v[224:225], 0, s[14:15]
	global_load_lds_dwordx4 v[160:161], off
	s_waitcnt vmcnt(8) lgkmcnt(0)
	s_barrier
	v_mfma_f32_16x16x32_bf16 v[60:63], v[148:151], v[190:193], v[60:63]
	v_mfma_f32_16x16x32_bf16 v[56:59], v[156:159], v[190:193], v[56:59]
	v_mfma_f32_16x16x32_bf16 v[44:47], v[148:151], v[198:201], v[44:47]
	v_mfma_f32_16x16x32_bf16 v[40:43], v[156:159], v[198:201], v[40:43]
	v_mfma_f32_16x16x32_bf16 v[28:31], v[148:151], v[206:209], v[28:31]
	v_mfma_f32_16x16x32_bf16 v[24:27], v[156:159], v[206:209], v[24:27]
	v_mfma_f32_16x16x32_bf16 v[12:15], v[148:151], v[214:217], v[12:15]
	v_mfma_f32_16x16x32_bf16 v[8:11], v[156:159], v[214:217], v[8:11]
	v_mfma_f32_16x16x32_bf16 v[60:63], v[152:155], v[194:197], v[60:63]
	v_mfma_f32_16x16x32_bf16 v[56:59], v[164:167], v[194:197], v[56:59]
	v_mfma_f32_16x16x32_bf16 v[44:47], v[152:155], v[202:205], v[44:47]
	v_mfma_f32_16x16x32_bf16 v[40:43], v[164:167], v[202:205], v[40:43]
	v_mfma_f32_16x16x32_bf16 v[28:31], v[152:155], v[210:213], v[28:31]
	v_mfma_f32_16x16x32_bf16 v[24:27], v[164:167], v[210:213], v[24:27]
	v_mfma_f32_16x16x32_bf16 v[12:15], v[152:155], v[218:221], v[12:15]
	v_mfma_f32_16x16x32_bf16 v[8:11], v[164:167], v[218:221], v[8:11]
	v_mfma_f32_16x16x32_bf16 v[52:55], v[174:177], v[190:193], v[52:55]
	v_mfma_f32_16x16x32_bf16 v[48:51], v[182:185], v[190:193], v[48:51]
	v_mfma_f32_16x16x32_bf16 v[36:39], v[174:177], v[198:201], v[36:39]
	v_mfma_f32_16x16x32_bf16 v[32:35], v[182:185], v[198:201], v[32:35]
	v_mfma_f32_16x16x32_bf16 v[20:23], v[174:177], v[206:209], v[20:23]
	v_mfma_f32_16x16x32_bf16 v[16:19], v[182:185], v[206:209], v[16:19]
	v_mfma_f32_16x16x32_bf16 v[4:7], v[174:177], v[214:217], v[4:7]
	v_mfma_f32_16x16x32_bf16 v[0:3], v[182:185], v[214:217], v[0:3]
	v_mfma_f32_16x16x32_bf16 v[52:55], v[178:181], v[194:197], v[52:55]
	v_mfma_f32_16x16x32_bf16 v[48:51], v[186:189], v[194:197], v[48:51]
	v_mfma_f32_16x16x32_bf16 v[36:39], v[178:181], v[202:205], v[36:39]
	v_mfma_f32_16x16x32_bf16 v[32:35], v[186:189], v[202:205], v[32:35]
	v_mfma_f32_16x16x32_bf16 v[20:23], v[178:181], v[210:213], v[20:23]
	v_mfma_f32_16x16x32_bf16 v[16:19], v[186:189], v[210:213], v[16:19]
	v_mfma_f32_16x16x32_bf16 v[4:7], v[178:181], v[218:221], v[4:7]
	v_mfma_f32_16x16x32_bf16 v[0:3], v[186:189], v[218:221], v[0:3]
	s_barrier
	s_add_i32 s46, s46, 2
	s_add_u32 s18, s18, 0x100
	s_addc_u32 s19, s19, 0
	s_cmp_gt_u32 s46, 41
	s_cbranch_scc0 .LBB0_1042
	s_add_u32 s18, s44, 0xffffff00
	s_addc_u32 s19, s45, -1
	s_and_b64 vcc, exec, s[2:3]
	s_cbranch_vccnz .LBB0_1045
	v_mov_b64_e32 v[0:1], 0
	s_mov_b32 s10, s41
	s_mov_b32 s24, s42
	s_mov_b64 s[12:13], s[16:17]
	s_mov_b32 s36, s43
	v_mov_b64_e32 v[2:3], 0
	v_mov_b64_e32 v[4:5], 0
	v_mov_b64_e32 v[6:7], 0
	v_mov_b64_e32 v[16:17], 0
	v_mov_b64_e32 v[18:19], 0
	v_mov_b64_e32 v[20:21], 0
	v_mov_b64_e32 v[22:23], 0
	v_mov_b64_e32 v[32:33], 0
	v_mov_b64_e32 v[34:35], 0
	v_mov_b64_e32 v[36:37], 0
	v_mov_b64_e32 v[38:39], 0
	v_mov_b64_e32 v[48:49], 0
	v_mov_b64_e32 v[50:51], 0
	v_mov_b64_e32 v[52:53], 0
	v_mov_b64_e32 v[54:55], 0
	v_mov_b64_e32 v[8:9], 0
	v_mov_b64_e32 v[10:11], 0
	v_mov_b64_e32 v[12:13], 0
	v_mov_b64_e32 v[14:15], 0
	v_mov_b64_e32 v[24:25], 0
	v_mov_b64_e32 v[26:27], 0
	v_mov_b64_e32 v[28:29], 0
	v_mov_b64_e32 v[30:31], 0
	v_mov_b64_e32 v[40:41], 0
	v_mov_b64_e32 v[42:43], 0
	v_mov_b64_e32 v[44:45], 0
	v_mov_b64_e32 v[46:47], 0
	v_mov_b64_e32 v[56:57], 0
	v_mov_b64_e32 v[58:59], 0
	v_mov_b64_e32 v[60:61], 0
	v_mov_b64_e32 v[62:63], 0
	v_mov_b64_e32 v[64:65], 0
	v_mov_b64_e32 v[66:67], 0
	v_mov_b64_e32 v[68:69], 0
	v_mov_b64_e32 v[70:71], 0
	v_mov_b64_e32 v[72:73], 0
	v_mov_b64_e32 v[74:75], 0
	v_mov_b64_e32 v[84:85], 0
	v_mov_b64_e32 v[86:87], 0
	v_mov_b64_e32 v[80:81], 0
	v_mov_b64_e32 v[82:83], 0
	v_mov_b64_e32 v[88:89], 0
	v_mov_b64_e32 v[90:91], 0
	v_mov_b64_e32 v[108:109], 0
	v_mov_b64_e32 v[110:111], 0
	v_mov_b64_e32 v[112:113], 0
	v_mov_b64_e32 v[114:115], 0
	v_mov_b64_e32 v[76:77], 0
	v_mov_b64_e32 v[78:79], 0
	v_mov_b64_e32 v[96:97], 0
	v_mov_b64_e32 v[98:99], 0
	v_mov_b64_e32 v[92:93], 0
	v_mov_b64_e32 v[94:95], 0
	v_mov_b64_e32 v[104:105], 0
	v_mov_b64_e32 v[106:107], 0
	v_mov_b64_e32 v[100:101], 0
	v_mov_b64_e32 v[102:103], 0
	v_mov_b64_e32 v[116:117], 0
	v_mov_b64_e32 v[118:119], 0
	v_mov_b64_e32 v[120:121], 0
	v_mov_b64_e32 v[122:123], 0
	v_mov_b64_e32 v[124:125], 0
	v_mov_b64_e32 v[126:127], 0
	s_andn2_b64 vcc, exec, s[0:1]
	s_cbranch_vccnz .LBB0_1046
	s_branch .LBB0_1047
